# counted vmcnt waits in mixer stage 1a (consume each z-row load pair as it lands); LN-stage wait no longer covers the unused warm load
# speedup vs baseline: 1.0063x; 1.0005x over previous
; #define LAS __attribute__((address_space(3)))
; __device__ __forceinline__ unsigned pk2(float lo, float hi) { unsigned r; asm("v_cvt_pk_bf16_f32 %0, %1, %2" : "=v"(r) : "v"(lo), "v"(hi)); return r; }
; __device__ __forceinline__ float bf_lo(unsigned w) { return __uint_as_float(w << 16); }
; __device__ __forceinline__ float bf_hi(unsigned w) { return __uint_as_float(w & 0xffff0000u); }
; __device__ __forceinline__ float sigmoidf_(float x) { return fast_rcp(1.0f + fast_exp2(-1.4426950408889634f * x)); }
; __device__ __forceinline__ void mixer_chunk(KP p, LAS unsigned char* lds, int l, int chunk) {
;     ...
;         u32x4 av[5], gv[5];
; #pragma unroll
;         for (int i = 0; i < 5; ++i) {
;             const int q = tid + 512 * (5 * half + i); int r = q >> 5; r = r < 158 ? r : 157; const int cc = (q & 31) * 8;
;             const int rr = (s0 - 30 + r >= 0) ? (c0 - 30 + r) : c0;
;             const bf16_t* zq = zb + (size_t)rr * DIN_P + cc; av[i] = *(const u32x4*)zq; gv[i] = *(const u32x4*)(zq + ZC_G);
;         }
;         pin(av); pin(gv);
; #pragma unroll
;         for (int i = 0; i < 5; ++i) {
;             const int q = tid + 512 * (5 * half + i); const int r = q >> 5, cc = (q & 31) * 8;
;             u32x4 o;
; #pragma unroll
;             for (int e = 0; e < 4; ++e) o[e] = pk2(bf_lo(av[i][e]) * sigmoidf_(bf_lo(gv[i][e])), bf_hi(av[i][e]) * sigmoidf_(bf_hi(gv[i][e])));
;             if (s0 - 30 + r < 0) o = (u32x4){0u, 0u, 0u, 0u};
;             if (r < 158) *(LAS u32x4*)(Y + r * YLD + cc) = o;
;         }
.LBB0_284:
	v_add_u32_e32 v0, s40, v204
	v_ashrrev_i32_e32 v47, 5, v0
	v_min_i32_e32 v0, 0x9d, v47
	v_add_u32_e32 v2, s18, v0
	v_cmp_gt_i32_e32 vcc, s42, v0
	v_mov_b32_e32 v4, s25
	s_nop 0
	v_cndmask_b32_e32 v0, v2, v4, vcc
	v_mad_i64_i32 v[2:3], s[46:47], v0, s65, v[42:43]
	v_add_u32_e32 v0, s40, v206
	v_ashrrev_i32_e32 v46, 5, v0
	v_min_i32_e32 v0, 0x9d, v46
	global_load_dwordx4 v[38:41], v[2:3], off
	global_load_dwordx4 v[34:37], v[2:3], off offset:512
	v_add_u32_e32 v2, s18, v0
	v_cmp_gt_i32_e32 vcc, s42, v0
	s_nop 1
	v_cndmask_b32_e32 v0, v2, v4, vcc
	v_mad_i64_i32 v[2:3], s[46:47], v0, s65, v[42:43]
	v_add_u32_e32 v0, s40, v212
	v_ashrrev_i32_e32 v45, 5, v0
	v_min_i32_e32 v0, 0x9d, v45
	global_load_dwordx4 v[26:29], v[2:3], off
	global_load_dwordx4 v[30:33], v[2:3], off offset:512
	v_add_u32_e32 v2, s18, v0
	v_cmp_gt_i32_e32 vcc, s42, v0
	s_nop 1
	v_cndmask_b32_e32 v0, v2, v4, vcc
	v_mad_i64_i32 v[2:3], s[46:47], v0, s65, v[42:43]
	v_add_u32_e32 v0, s40, v211
	v_ashrrev_i32_e32 v44, 5, v0
	v_min_i32_e32 v0, 0x9d, v44
	global_load_dwordx4 v[18:21], v[2:3], off
	global_load_dwordx4 v[22:25], v[2:3], off offset:512
	v_add_u32_e32 v2, s18, v0
	v_cmp_gt_i32_e32 vcc, s42, v0
	s_nop 1
	v_cndmask_b32_e32 v0, v2, v4, vcc
	v_mad_i64_i32 v[2:3], s[46:47], v0, s65, v[42:43]
	v_add_u32_e32 v0, s40, v210
	v_ashrrev_i32_e32 v0, 5, v0
	global_load_dwordx4 v[10:13], v[2:3], off
	global_load_dwordx4 v[14:17], v[2:3], off offset:512
	v_min_i32_e32 v2, 0x9d, v0
	v_add_u32_e32 v3, s18, v2
	v_cmp_gt_i32_e32 vcc, s42, v2
	s_nop 1
	v_cndmask_b32_e32 v2, v3, v4, vcc
	v_mad_i64_i32 v[6:7], s[40:41], v2, s65, v[42:43]
	global_load_dwordx4 v[2:5], v[6:7], off
	s_nop 0
	global_load_dwordx4 v[6:9], v[6:7], off offset:512
	v_cmp_gt_i32_e32 vcc, s66, v47
	s_waitcnt vmcnt(8)
	v_lshlrev_b32_e32 v48, 16, v38
	v_lshlrev_b32_e32 v49, 16, v34
	v_and_b32_e32 v34, 0xffff0000, v34
	v_mul_f32_e32 v49, 0xbfb8aa3b, v49
	v_mul_f32_e32 v34, 0xbfb8aa3b, v34
	v_exp_f32_e32 v49, v49
	v_exp_f32_e32 v34, v34
	v_and_b32_e32 v38, 0xffff0000, v38
	v_add_f32_e32 v49, 1.0, v49
	v_add_f32_e32 v34, 1.0, v34
	v_rcp_f32_e32 v49, v49
	v_rcp_f32_e32 v34, v34
	v_mul_f32_e32 v48, v49, v48
	v_mul_f32_e32 v34, v34, v38
	v_cvt_pk_bf16_f32 v34, v48, v34
	v_lshlrev_b32_e32 v48, 16, v35
	v_and_b32_e32 v35, 0xffff0000, v35
	v_mul_f32_e32 v35, 0xbfb8aa3b, v35
	v_exp_f32_e32 v35, v35
	v_lshlrev_b32_e32 v38, 16, v39
	v_mul_f32_e32 v48, 0xbfb8aa3b, v48
	v_and_b32_e32 v39, 0xffff0000, v39
	v_add_f32_e32 v35, 1.0, v35
	v_rcp_f32_e32 v35, v35
	v_exp_f32_e32 v48, v48
	v_mul_f32_e32 v35, v35, v39
	v_lshlrev_b32_e32 v39, 16, v36
	v_mul_f32_e32 v39, 0xbfb8aa3b, v39
	v_and_b32_e32 v36, 0xffff0000, v36
	v_exp_f32_e32 v39, v39
	v_mul_f32_e32 v36, 0xbfb8aa3b, v36
	v_exp_f32_e32 v36, v36
	v_add_f32_e32 v48, 1.0, v48
	v_rcp_f32_e32 v48, v48
	v_add_f32_e32 v39, 1.0, v39
	v_rcp_f32_e32 v39, v39
	v_add_f32_e32 v36, 1.0, v36
	v_rcp_f32_e32 v36, v36
	v_mul_f32_e32 v38, v48, v38
	v_cvt_pk_bf16_f32 v35, v38, v35
	v_lshlrev_b32_e32 v38, 16, v40
	v_mul_f32_e32 v38, v39, v38
	v_and_b32_e32 v39, 0xffff0000, v40
	v_mul_f32_e32 v36, v36, v39
	v_lshlrev_b32_e32 v39, 16, v37
	v_mul_f32_e32 v39, 0xbfb8aa3b, v39
	v_and_b32_e32 v37, 0xffff0000, v37
	v_exp_f32_e32 v39, v39
	v_mul_f32_e32 v37, 0xbfb8aa3b, v37
	v_exp_f32_e32 v37, v37
	v_cvt_pk_bf16_f32 v36, v38, v36
	v_add_f32_e32 v39, 1.0, v39
	v_rcp_f32_e32 v39, v39
	v_add_f32_e32 v37, 1.0, v37
	v_rcp_f32_e32 v37, v37
	v_lshlrev_b32_e32 v38, 16, v41
	v_mul_f32_e32 v38, v39, v38
	v_and_b32_e32 v39, 0xffff0000, v41
	v_mul_f32_e32 v37, v37, v39
	v_cvt_pk_bf16_f32 v37, v38, v37
	s_and_saveexec_b64 s[40:41], vcc
	s_cbranch_execz .LBB0_286
	v_cmp_le_i32_e32 vcc, s42, v47
	v_mad_u64_u32 v[38:39], s[46:47], v47, s67, v[166:167]
	s_nop 0
	v_cndmask_b32_e32 v37, 0, v37, vcc
	v_cndmask_b32_e32 v36, 0, v36, vcc
	v_cndmask_b32_e32 v35, 0, v35, vcc
	v_cndmask_b32_e32 v34, 0, v34, vcc
	ds_write_b128 v38, v[34:37]
.LBB0_286:
	s_or_b64 exec, exec, s[40:41]
	s_waitcnt vmcnt(6)
	v_lshlrev_b32_e32 v34, 16, v30
	v_and_b32_e32 v30, 0xffff0000, v30
	v_mul_f32_e32 v30, 0xbfb8aa3b, v30
	v_exp_f32_e32 v30, v30
	v_mul_f32_e32 v34, 0xbfb8aa3b, v34
	v_lshlrev_b32_e32 v35, 16, v26
	v_and_b32_e32 v26, 0xffff0000, v26
	v_add_f32_e32 v30, 1.0, v30
	v_rcp_f32_e32 v30, v30
	v_exp_f32_e32 v34, v34
	v_cmp_gt_i32_e32 vcc, s66, v46
	v_mul_f32_e32 v26, v30, v26
	v_lshlrev_b32_e32 v30, 16, v31
	v_and_b32_e32 v31, 0xffff0000, v31
	v_mul_f32_e32 v31, 0xbfb8aa3b, v31
	v_exp_f32_e32 v31, v31
	v_add_f32_e32 v34, 1.0, v34
	v_rcp_f32_e32 v34, v34
	v_mul_f32_e32 v30, 0xbfb8aa3b, v30
	v_add_f32_e32 v31, 1.0, v31
	v_exp_f32_e32 v30, v30
	v_rcp_f32_e32 v31, v31
	v_mul_f32_e32 v34, v34, v35
	v_cvt_pk_bf16_f32 v26, v34, v26
	v_lshlrev_b32_e32 v34, 16, v27
	v_and_b32_e32 v27, 0xffff0000, v27
	v_add_f32_e32 v30, 1.0, v30
	v_mul_f32_e32 v27, v31, v27
	v_lshlrev_b32_e32 v31, 16, v32
	v_and_b32_e32 v32, 0xffff0000, v32
	v_rcp_f32_e32 v30, v30
	v_mul_f32_e32 v31, 0xbfb8aa3b, v31
	v_mul_f32_e32 v32, 0xbfb8aa3b, v32
	v_exp_f32_e32 v31, v31
	v_exp_f32_e32 v32, v32
	v_mul_f32_e32 v30, v30, v34
	v_cvt_pk_bf16_f32 v27, v30, v27
	v_add_f32_e32 v30, 1.0, v31
	v_add_f32_e32 v31, 1.0, v32
	v_rcp_f32_e32 v30, v30
	v_rcp_f32_e32 v31, v31
	v_lshlrev_b32_e32 v32, 16, v28
	v_and_b32_e32 v28, 0xffff0000, v28
	v_mul_f32_e32 v30, v30, v32
	v_mul_f32_e32 v28, v31, v28
	v_lshlrev_b32_e32 v31, 16, v33
	v_and_b32_e32 v32, 0xffff0000, v33
	v_mul_f32_e32 v31, 0xbfb8aa3b, v31
	v_mul_f32_e32 v32, 0xbfb8aa3b, v32
	v_exp_f32_e32 v31, v31
	v_exp_f32_e32 v32, v32
	v_cvt_pk_bf16_f32 v28, v30, v28
	v_add_f32_e32 v30, 1.0, v31
	v_add_f32_e32 v31, 1.0, v32
	v_rcp_f32_e32 v31, v31
	v_rcp_f32_e32 v30, v30
	v_lshlrev_b32_e32 v32, 16, v29
	v_and_b32_e32 v29, 0xffff0000, v29
	v_mul_f32_e32 v29, v31, v29
	v_mul_f32_e32 v30, v30, v32
	v_cvt_pk_bf16_f32 v29, v30, v29
	s_and_saveexec_b64 s[40:41], vcc
	s_cbranch_execz .LBB0_288
	v_cmp_le_i32_e32 vcc, s42, v46
	v_mad_u64_u32 v[30:31], s[46:47], v46, s67, v[166:167]
	s_nop 0
	v_cndmask_b32_e32 v29, 0, v29, vcc
	v_cndmask_b32_e32 v28, 0, v28, vcc
	v_cndmask_b32_e32 v27, 0, v27, vcc
	v_cndmask_b32_e32 v26, 0, v26, vcc
	ds_write_b128 v30, v[26:29]
; #define LAS __attribute__((address_space(3)))
; __device__ __forceinline__ unsigned pk2(float lo, float hi) { unsigned r; asm("v_cvt_pk_bf16_f32 %0, %1, %2" : "=v"(r) : "v"(lo), "v"(hi)); return r; }
; __device__ __forceinline__ float bf_lo(unsigned w) { return __uint_as_float(w << 16); }
; __device__ __forceinline__ float bf_hi(unsigned w) { return __uint_as_float(w & 0xffff0000u); }
; __device__ __forceinline__ float sigmoidf_(float x) { return fast_rcp(1.0f + fast_exp2(-1.4426950408889634f * x)); }
; __device__ __forceinline__ void mixer_chunk(KP p, LAS unsigned char* lds, int l, int chunk) {
;     ...
;         for (int i = 0; i < 5; ++i) {
;             const int q = tid + 512 * (5 * half + i); const int r = q >> 5, cc = (q & 31) * 8;
;             u32x4 o;
; #pragma unroll
;             for (int e = 0; e < 4; ++e) o[e] = pk2(bf_lo(av[i][e]) * sigmoidf_(bf_lo(gv[i][e])), bf_hi(av[i][e]) * sigmoidf_(bf_hi(gv[i][e])));
;             if (s0 - 30 + r < 0) o = (u32x4){0u, 0u, 0u, 0u};
;             if (r < 158) *(LAS u32x4*)(Y + r * YLD + cc) = o;
;         }
.LBB0_288:
	s_or_b64 exec, exec, s[40:41]
	s_waitcnt vmcnt(4)
	v_lshlrev_b32_e32 v26, 16, v22
	v_and_b32_e32 v22, 0xffff0000, v22
	v_mul_f32_e32 v22, 0xbfb8aa3b, v22
	v_exp_f32_e32 v22, v22
	v_mul_f32_e32 v26, 0xbfb8aa3b, v26
	v_lshlrev_b32_e32 v27, 16, v18
	v_and_b32_e32 v18, 0xffff0000, v18
	v_add_f32_e32 v22, 1.0, v22
	v_rcp_f32_e32 v22, v22
	v_exp_f32_e32 v26, v26
	v_cmp_gt_i32_e32 vcc, s66, v45
	v_mul_f32_e32 v18, v22, v18
	v_lshlrev_b32_e32 v22, 16, v23
	v_and_b32_e32 v23, 0xffff0000, v23
	v_mul_f32_e32 v23, 0xbfb8aa3b, v23
	v_exp_f32_e32 v23, v23
	v_add_f32_e32 v26, 1.0, v26
	v_rcp_f32_e32 v26, v26
	v_mul_f32_e32 v22, 0xbfb8aa3b, v22
	v_add_f32_e32 v23, 1.0, v23
	v_exp_f32_e32 v22, v22
	v_rcp_f32_e32 v23, v23
	v_mul_f32_e32 v26, v26, v27
	v_cvt_pk_bf16_f32 v18, v26, v18
	v_lshlrev_b32_e32 v26, 16, v19
	v_and_b32_e32 v19, 0xffff0000, v19
	v_add_f32_e32 v22, 1.0, v22
	v_mul_f32_e32 v19, v23, v19
	v_lshlrev_b32_e32 v23, 16, v24
	v_and_b32_e32 v24, 0xffff0000, v24
	v_rcp_f32_e32 v22, v22
	v_mul_f32_e32 v23, 0xbfb8aa3b, v23
	v_mul_f32_e32 v24, 0xbfb8aa3b, v24
	v_exp_f32_e32 v23, v23
	v_exp_f32_e32 v24, v24
	v_mul_f32_e32 v22, v22, v26
	v_cvt_pk_bf16_f32 v19, v22, v19
	v_add_f32_e32 v22, 1.0, v23
	v_add_f32_e32 v23, 1.0, v24
	v_rcp_f32_e32 v22, v22
	v_rcp_f32_e32 v23, v23
	v_lshlrev_b32_e32 v24, 16, v20
	v_and_b32_e32 v20, 0xffff0000, v20
	v_mul_f32_e32 v22, v22, v24
	v_mul_f32_e32 v20, v23, v20
	v_lshlrev_b32_e32 v23, 16, v25
	v_and_b32_e32 v24, 0xffff0000, v25
	v_mul_f32_e32 v23, 0xbfb8aa3b, v23
	v_mul_f32_e32 v24, 0xbfb8aa3b, v24
	v_exp_f32_e32 v23, v23
	v_exp_f32_e32 v24, v24
	v_cvt_pk_bf16_f32 v20, v22, v20
	v_add_f32_e32 v22, 1.0, v23
	v_add_f32_e32 v23, 1.0, v24
	v_rcp_f32_e32 v23, v23
	v_rcp_f32_e32 v22, v22
	v_lshlrev_b32_e32 v24, 16, v21
	v_and_b32_e32 v21, 0xffff0000, v21
	v_mul_f32_e32 v21, v23, v21
	v_mul_f32_e32 v22, v22, v24
	v_cvt_pk_bf16_f32 v21, v22, v21
	s_and_saveexec_b64 s[40:41], vcc
	s_cbranch_execz .LBB0_290
	v_cmp_le_i32_e32 vcc, s42, v45
	v_mad_u64_u32 v[22:23], s[46:47], v45, s67, v[166:167]
	s_nop 0
	v_cndmask_b32_e32 v21, 0, v21, vcc
	v_cndmask_b32_e32 v20, 0, v20, vcc
	v_cndmask_b32_e32 v19, 0, v19, vcc
	v_cndmask_b32_e32 v18, 0, v18, vcc
	ds_write_b128 v22, v[18:21]
.LBB0_290:
	s_or_b64 exec, exec, s[40:41]
	s_waitcnt vmcnt(2)
	v_lshlrev_b32_e32 v18, 16, v14
	v_and_b32_e32 v14, 0xffff0000, v14
	v_mul_f32_e32 v14, 0xbfb8aa3b, v14
	v_exp_f32_e32 v14, v14
	v_mul_f32_e32 v18, 0xbfb8aa3b, v18
	v_lshlrev_b32_e32 v19, 16, v10
	v_and_b32_e32 v10, 0xffff0000, v10
	v_add_f32_e32 v14, 1.0, v14
	v_rcp_f32_e32 v14, v14
	v_exp_f32_e32 v18, v18
	v_cmp_gt_i32_e32 vcc, s66, v44
	v_mul_f32_e32 v10, v14, v10
	v_lshlrev_b32_e32 v14, 16, v15
	v_and_b32_e32 v15, 0xffff0000, v15
	v_mul_f32_e32 v15, 0xbfb8aa3b, v15
	v_exp_f32_e32 v15, v15
	v_add_f32_e32 v18, 1.0, v18
	v_rcp_f32_e32 v18, v18
	v_mul_f32_e32 v14, 0xbfb8aa3b, v14
	v_add_f32_e32 v15, 1.0, v15
	v_exp_f32_e32 v14, v14
	v_rcp_f32_e32 v15, v15
	v_mul_f32_e32 v18, v18, v19
	v_cvt_pk_bf16_f32 v10, v18, v10
	v_lshlrev_b32_e32 v18, 16, v11
	v_and_b32_e32 v11, 0xffff0000, v11
	v_add_f32_e32 v14, 1.0, v14
	v_mul_f32_e32 v11, v15, v11
	v_lshlrev_b32_e32 v15, 16, v16
	v_and_b32_e32 v16, 0xffff0000, v16
	v_rcp_f32_e32 v14, v14
	v_mul_f32_e32 v15, 0xbfb8aa3b, v15
	v_mul_f32_e32 v16, 0xbfb8aa3b, v16
	v_exp_f32_e32 v15, v15
	v_exp_f32_e32 v16, v16
	v_mul_f32_e32 v14, v14, v18
	v_cvt_pk_bf16_f32 v11, v14, v11
	v_add_f32_e32 v14, 1.0, v15
	v_add_f32_e32 v15, 1.0, v16
	v_rcp_f32_e32 v14, v14
	v_rcp_f32_e32 v15, v15
	v_lshlrev_b32_e32 v16, 16, v12
	v_and_b32_e32 v12, 0xffff0000, v12
	v_mul_f32_e32 v14, v14, v16
	v_mul_f32_e32 v12, v15, v12
	v_lshlrev_b32_e32 v15, 16, v17
	v_and_b32_e32 v16, 0xffff0000, v17
	v_mul_f32_e32 v15, 0xbfb8aa3b, v15
	v_mul_f32_e32 v16, 0xbfb8aa3b, v16
	v_exp_f32_e32 v15, v15
	v_exp_f32_e32 v16, v16
	v_cvt_pk_bf16_f32 v12, v14, v12
	v_add_f32_e32 v14, 1.0, v15
	v_add_f32_e32 v15, 1.0, v16
	v_rcp_f32_e32 v15, v15
	v_rcp_f32_e32 v14, v14
	v_lshlrev_b32_e32 v16, 16, v13
	v_and_b32_e32 v13, 0xffff0000, v13
	v_mul_f32_e32 v13, v15, v13
	v_mul_f32_e32 v14, v14, v16
	v_cvt_pk_bf16_f32 v13, v14, v13
	s_and_saveexec_b64 s[40:41], vcc
	s_cbranch_execz .LBB0_292
	v_cmp_le_i32_e32 vcc, s42, v44
	v_mad_u64_u32 v[14:15], s[46:47], v44, s67, v[166:167]
	s_nop 0
	v_cndmask_b32_e32 v13, 0, v13, vcc
	v_cndmask_b32_e32 v12, 0, v12, vcc
	v_cndmask_b32_e32 v11, 0, v11, vcc
	v_cndmask_b32_e32 v10, 0, v10, vcc
	ds_write_b128 v14, v[10:13]
.LBB0_292:
	s_or_b64 exec, exec, s[40:41]
	s_waitcnt vmcnt(0)
	v_lshlrev_b32_e32 v10, 16, v6
	v_and_b32_e32 v6, 0xffff0000, v6
	v_mul_f32_e32 v6, 0xbfb8aa3b, v6
	v_exp_f32_e32 v6, v6
	v_mul_f32_e32 v10, 0xbfb8aa3b, v10
	v_lshlrev_b32_e32 v11, 16, v2
	v_and_b32_e32 v2, 0xffff0000, v2
	v_add_f32_e32 v6, 1.0, v6
	v_rcp_f32_e32 v6, v6
	v_exp_f32_e32 v10, v10
	v_cmp_gt_i32_e32 vcc, s66, v0
	v_mul_f32_e32 v2, v6, v2
	v_lshlrev_b32_e32 v6, 16, v7
	v_and_b32_e32 v7, 0xffff0000, v7
	v_mul_f32_e32 v7, 0xbfb8aa3b, v7
	v_exp_f32_e32 v7, v7
	v_add_f32_e32 v10, 1.0, v10
	v_rcp_f32_e32 v10, v10
	v_mul_f32_e32 v6, 0xbfb8aa3b, v6
	v_add_f32_e32 v7, 1.0, v7
	v_exp_f32_e32 v6, v6
	v_rcp_f32_e32 v7, v7
	v_mul_f32_e32 v10, v10, v11
	v_cvt_pk_bf16_f32 v2, v10, v2
	v_lshlrev_b32_e32 v10, 16, v3
	v_and_b32_e32 v3, 0xffff0000, v3
	v_add_f32_e32 v6, 1.0, v6
	v_mul_f32_e32 v3, v7, v3
	v_lshlrev_b32_e32 v7, 16, v8
	v_and_b32_e32 v8, 0xffff0000, v8
	v_rcp_f32_e32 v6, v6
	v_mul_f32_e32 v7, 0xbfb8aa3b, v7
	v_mul_f32_e32 v8, 0xbfb8aa3b, v8
	v_exp_f32_e32 v7, v7
	v_exp_f32_e32 v8, v8
	v_mul_f32_e32 v6, v6, v10
	v_cvt_pk_bf16_f32 v3, v6, v3
	v_add_f32_e32 v6, 1.0, v7
	v_add_f32_e32 v7, 1.0, v8
	v_rcp_f32_e32 v6, v6
	v_rcp_f32_e32 v7, v7
	v_lshlrev_b32_e32 v8, 16, v4
	v_and_b32_e32 v4, 0xffff0000, v4
	v_mul_f32_e32 v6, v6, v8
	v_mul_f32_e32 v4, v7, v4
	v_lshlrev_b32_e32 v7, 16, v9
	v_and_b32_e32 v8, 0xffff0000, v9
	v_mul_f32_e32 v7, 0xbfb8aa3b, v7
	v_mul_f32_e32 v8, 0xbfb8aa3b, v8
	v_exp_f32_e32 v7, v7
	v_exp_f32_e32 v8, v8
	v_cvt_pk_bf16_f32 v4, v6, v4
	v_add_f32_e32 v6, 1.0, v7
	v_add_f32_e32 v7, 1.0, v8
	v_rcp_f32_e32 v7, v7
	v_rcp_f32_e32 v6, v6
	v_lshlrev_b32_e32 v8, 16, v5
	v_and_b32_e32 v5, 0xffff0000, v5
	v_mul_f32_e32 v5, v7, v5
	v_mul_f32_e32 v6, v6, v8
	v_cvt_pk_bf16_f32 v5, v6, v5
	s_and_saveexec_b64 s[40:41], vcc
	s_cbranch_execz .LBB0_283
	v_cmp_le_i32_e32 vcc, s42, v0
	v_mad_u64_u32 v[6:7], s[46:47], v0, s67, v[166:167]
	s_nop 0
	v_cndmask_b32_e32 v5, 0, v5, vcc
	v_cndmask_b32_e32 v4, 0, v4, vcc
	v_cndmask_b32_e32 v3, 0, v3, vcc
	v_cndmask_b32_e32 v2, 0, v2, vcc
	ds_write_b128 v6, v[2:5]
	s_branch .LBB0_283

; #define LAS __attribute__((address_space(3)))
; __device__ __forceinline__ float bf_lo(unsigned w) { return __uint_as_float(w << 16); }
; __device__ __forceinline__ float bf_hi(unsigned w) { return __uint_as_float(w & 0xffff0000u); }
; __device__ __forceinline__ void mixer_chunk(KP p, LAS unsigned char* lds, int l, int chunk) {
;     ...
;         for (int half = 0; half < 2; ++half) {
;             f32x4 x[8]; float s[8];
; #pragma unroll
;             for (int i = 0; i < 8; ++i) { const u32x2 v = *(const LAS u32x2*)(CO + (16 * w + 8 * half + i) * YLD + 4 * lane);
;                 x[i] = (f32x4){bf_lo(v.x), bf_hi(v.x), bf_lo(v.y), bf_hi(v.y)}; s[i] = (x[i][0] + x[i][1]) + (x[i][2] + x[i][3]); }
; #pragma unroll
;             for (int o = 1; o < 64; o <<= 1)
; #pragma unroll
;                 for (int i = 0; i < 8; ++i) s[i] += __shfl_xor(s[i], o);
; #pragma unroll
;             for (int i = 0; i < 8; ++i) { x[i] = x[i] - s[i] * (1.0f / 256.0f); s[i] = (x[i][0] * x[i][0] + x[i][1] * x[i][1]) + (x[i][2] * x[i][2] + x[i][3] * x[i][3]); }
; #pragma unroll
;             for (int o = 1; o < 64; o <<= 1)
; #pragma unroll
;                 for (int i = 0; i < 8; ++i) s[i] += __shfl_xor(s[i], o);
.LBB0_297:
	s_or_b32 s6, s6, s88
	s_mulk_i32 s6, 0x210
	v_cndmask_b32_e64 v50, 0, 1, s[40:41]
	v_add_u32_e32 v110, s6, v0
	v_cmp_ne_u32_e32 vcc, 1, v50
	ds_read2_b64 v[50:53], v110 offset1:66
	v_add_u32_e32 v93, 0x800, v110
	ds_read2_b64 v[66:69], v93 offset0:140 offset1:206
	s_mov_b32 s6, 8
	s_mov_b64 s[40:41], 0
	s_waitcnt lgkmcnt(1)
	v_lshlrev_b32_e32 v65, 16, v51
	v_lshlrev_b32_e32 v64, 16, v50
	v_and_b32_e32 v71, 0xffff0000, v51
	v_and_b32_e32 v70, 0xffff0000, v50
	v_pk_add_f32 v[50:51], v[64:65], v[70:71]
	v_lshlrev_b32_e32 v63, 16, v53
	v_lshlrev_b32_e32 v62, 16, v52
	v_and_b32_e32 v73, 0xffff0000, v53
	v_and_b32_e32 v72, 0xffff0000, v52
	v_add_f32_e32 v104, v50, v51
	v_pk_add_f32 v[50:51], v[62:63], v[72:73]
	s_waitcnt lgkmcnt(0)
	v_and_b32_e32 v103, 0xffff0000, v69
	v_add_f32_e32 v105, v50, v51
	ds_read2_b64 v[50:53], v110 offset0:132 offset1:198
	v_and_b32_e32 v102, 0xffff0000, v68
	s_and_b64 vcc, exec, vcc
	s_waitcnt lgkmcnt(0)
	v_lshlrev_b32_e32 v61, 16, v51
	v_lshlrev_b32_e32 v60, 16, v50
	v_and_b32_e32 v95, 0xffff0000, v51
	v_and_b32_e32 v94, 0xffff0000, v50
	v_pk_add_f32 v[50:51], v[60:61], v[94:95]
	v_lshlrev_b32_e32 v59, 16, v53
	v_lshlrev_b32_e32 v58, 16, v52
	v_and_b32_e32 v97, 0xffff0000, v53
	v_and_b32_e32 v96, 0xffff0000, v52
	v_add_f32_e32 v106, v50, v51
	v_pk_add_f32 v[50:51], v[58:59], v[96:97]
	s_nop 0
	v_add_f32_e32 v107, v50, v51
	ds_read2_b64 v[50:53], v93 offset0:8 offset1:74
	s_waitcnt lgkmcnt(0)
	v_lshlrev_b32_e32 v57, 16, v51
	v_lshlrev_b32_e32 v56, 16, v50
	v_and_b32_e32 v99, 0xffff0000, v51
	v_and_b32_e32 v98, 0xffff0000, v50
	v_pk_add_f32 v[50:51], v[56:57], v[98:99]
	v_lshlrev_b32_e32 v55, 16, v53
	v_lshlrev_b32_e32 v54, 16, v52
	v_and_b32_e32 v101, 0xffff0000, v53
	v_and_b32_e32 v100, 0xffff0000, v52
	v_add_f32_e32 v108, v50, v51
	v_pk_add_f32 v[50:51], v[54:55], v[100:101]
	v_lshlrev_b32_e32 v53, 16, v67
	v_lshlrev_b32_e32 v52, 16, v66
	v_and_b32_e32 v67, 0xffff0000, v67
	v_and_b32_e32 v66, 0xffff0000, v66
	v_add_f32_e32 v109, v50, v51
	v_pk_add_f32 v[50:51], v[52:53], v[66:67]
	s_nop 0
	v_add_f32_e32 v111, v50, v51
	v_lshlrev_b32_e32 v51, 16, v69
	v_lshlrev_b32_e32 v50, 16, v68
	v_pk_add_f32 v[68:69], v[50:51], v[102:103]
	s_nop 0
	v_add_f32_e32 v68, v68, v69
	ds_bpermute_b32 v69, v213, v104
	s_waitcnt lgkmcnt(0)
	v_add_f32_e32 v69, v104, v69
	ds_bpermute_b32 v104, v213, v105
	s_waitcnt lgkmcnt(0)
	v_add_f32_e32 v104, v105, v104
	ds_bpermute_b32 v105, v213, v106
	s_waitcnt lgkmcnt(0)
	v_add_f32_e32 v105, v106, v105
	ds_bpermute_b32 v106, v213, v107
	s_waitcnt lgkmcnt(0)
	v_add_f32_e32 v106, v107, v106
	ds_bpermute_b32 v107, v213, v108
	s_waitcnt lgkmcnt(0)
	v_add_f32_e32 v107, v108, v107
	ds_bpermute_b32 v108, v213, v109
	s_waitcnt lgkmcnt(0)
	v_add_f32_e32 v108, v109, v108
	ds_bpermute_b32 v109, v213, v111
	s_waitcnt lgkmcnt(0)
	v_add_f32_e32 v109, v111, v109
	ds_bpermute_b32 v111, v213, v68
	s_waitcnt lgkmcnt(0)
	v_add_f32_e32 v68, v68, v111
	ds_bpermute_b32 v111, v214, v69
	s_waitcnt lgkmcnt(0)
	v_add_f32_e32 v69, v69, v111
	ds_bpermute_b32 v111, v214, v104
	s_waitcnt lgkmcnt(0)
	v_add_f32_e32 v104, v104, v111
	ds_bpermute_b32 v111, v214, v105
	s_waitcnt lgkmcnt(0)
	v_add_f32_e32 v105, v105, v111
	ds_bpermute_b32 v111, v214, v106
	s_waitcnt lgkmcnt(0)
	v_add_f32_e32 v106, v106, v111
	ds_bpermute_b32 v111, v214, v107
	s_waitcnt lgkmcnt(0)
	v_add_f32_e32 v107, v107, v111
	ds_bpermute_b32 v111, v214, v108
	s_waitcnt lgkmcnt(0)
	v_add_f32_e32 v108, v108, v111
	ds_bpermute_b32 v111, v214, v109
	s_waitcnt lgkmcnt(0)
	v_add_f32_e32 v109, v109, v111
	ds_bpermute_b32 v111, v214, v68
	s_waitcnt lgkmcnt(0)
	v_add_f32_e32 v68, v68, v111
	ds_bpermute_b32 v111, v91, v69
	s_waitcnt lgkmcnt(0)
	v_add_f32_e32 v69, v69, v111
	ds_bpermute_b32 v111, v91, v104
	s_waitcnt lgkmcnt(0)
	v_add_f32_e32 v104, v104, v111
	ds_bpermute_b32 v111, v91, v105
	s_waitcnt lgkmcnt(0)
	v_add_f32_e32 v105, v105, v111
	ds_bpermute_b32 v111, v91, v106
	s_waitcnt lgkmcnt(0)
	v_add_f32_e32 v106, v106, v111
	ds_bpermute_b32 v111, v91, v107
	s_waitcnt lgkmcnt(0)
	v_add_f32_e32 v107, v107, v111
	ds_bpermute_b32 v111, v91, v108
	s_waitcnt lgkmcnt(0)
	v_add_f32_e32 v108, v108, v111
	ds_bpermute_b32 v111, v91, v109
	s_waitcnt lgkmcnt(0)
	v_add_f32_e32 v109, v109, v111
	ds_bpermute_b32 v111, v91, v68
	s_waitcnt lgkmcnt(0)
	v_add_f32_e32 v68, v68, v111
	ds_bpermute_b32 v111, v92, v69
	s_waitcnt lgkmcnt(0)
	v_add_f32_e32 v69, v69, v111
	ds_bpermute_b32 v111, v92, v104
	s_waitcnt lgkmcnt(0)
	v_add_f32_e32 v104, v104, v111
	ds_bpermute_b32 v111, v92, v105
	s_waitcnt lgkmcnt(0)
	v_add_f32_e32 v105, v105, v111
	ds_bpermute_b32 v111, v92, v106
	s_waitcnt lgkmcnt(0)
	v_add_f32_e32 v106, v106, v111
	ds_bpermute_b32 v111, v92, v107
	s_waitcnt lgkmcnt(0)
	v_add_f32_e32 v107, v107, v111
	ds_bpermute_b32 v111, v92, v108
	s_waitcnt lgkmcnt(0)
	v_add_f32_e32 v108, v108, v111
	ds_bpermute_b32 v111, v92, v109
	s_waitcnt lgkmcnt(0)
	v_add_f32_e32 v109, v109, v111
	ds_bpermute_b32 v111, v92, v68
	s_waitcnt lgkmcnt(0)
	v_add_f32_e32 v68, v68, v111
	ds_bpermute_b32 v111, v207, v69
	s_waitcnt lgkmcnt(0)
	v_add_f32_e32 v69, v69, v111
	ds_bpermute_b32 v111, v207, v104
	s_waitcnt lgkmcnt(0)
	v_add_f32_e32 v104, v104, v111
	ds_bpermute_b32 v111, v207, v105
	s_waitcnt lgkmcnt(0)
	v_add_f32_e32 v105, v105, v111
	ds_bpermute_b32 v111, v207, v106
	s_waitcnt lgkmcnt(0)
	v_add_f32_e32 v106, v106, v111
	ds_bpermute_b32 v111, v207, v107
	s_waitcnt lgkmcnt(0)
	v_add_f32_e32 v107, v107, v111
	ds_bpermute_b32 v111, v207, v108
	s_waitcnt lgkmcnt(0)
	v_add_f32_e32 v108, v108, v111
	ds_bpermute_b32 v111, v207, v109
	s_waitcnt lgkmcnt(0)
	v_add_f32_e32 v109, v109, v111
	ds_bpermute_b32 v111, v207, v68
	s_waitcnt lgkmcnt(0)
; __device__ __forceinline__ void mixer_chunk(KP p, LAS unsigned char* lds, int l, int chunk) {
;     ...
;             for (int i = 0; i < 8; ++i) { x[i] = x[i] - s[i] * (1.0f / 256.0f); s[i] = (x[i][0] * x[i][0] + x[i][1] * x[i][1]) + (x[i][2] * x[i][2] + x[i][3] * x[i][3]); }
; #pragma unroll
;             for (int o = 1; o < 64; o <<= 1)
; #pragma unroll
;                 for (int i = 0; i < 8; ++i) s[i] += __shfl_xor(s[i], o);
	v_add_f32_e32 v68, v68, v111
	ds_bpermute_b32 v111, v208, v69
	s_waitcnt lgkmcnt(0)
	v_add_f32_e32 v69, v69, v111
	ds_bpermute_b32 v111, v208, v104
	v_fmac_f32_e32 v70, 0xbb800000, v69
	v_fmac_f32_e32 v71, 0xbb800000, v69
	v_fmac_f32_e32 v65, 0xbb800000, v69
	v_fmac_f32_e32 v64, 0xbb800000, v69
	s_waitcnt lgkmcnt(0)
	v_add_f32_e32 v111, v104, v111
	ds_bpermute_b32 v104, v208, v105
	v_fmac_f32_e32 v72, 0xbb800000, v111
	v_fmac_f32_e32 v73, 0xbb800000, v111
	v_fmac_f32_e32 v63, 0xbb800000, v111
	v_fmac_f32_e32 v62, 0xbb800000, v111
	s_waitcnt lgkmcnt(0)
	v_add_f32_e32 v112, v105, v104
	ds_bpermute_b32 v104, v208, v106
	v_mov_b32_e32 v105, v71
	v_fmac_f32_e32 v94, 0xbb800000, v112
	v_fmac_f32_e32 v95, 0xbb800000, v112
	v_fmac_f32_e32 v61, 0xbb800000, v112
	s_waitcnt lgkmcnt(0)
	v_add_f32_e32 v113, v106, v104
	ds_bpermute_b32 v104, v208, v107
	v_fmac_f32_e32 v60, 0xbb800000, v112
	v_fmac_f32_e32 v96, 0xbb800000, v113
	v_fmac_f32_e32 v97, 0xbb800000, v113
	v_fmac_f32_e32 v59, 0xbb800000, v113
	s_waitcnt lgkmcnt(0)
	v_add_f32_e32 v114, v107, v104
	ds_bpermute_b32 v104, v208, v108
	v_fmac_f32_e32 v58, 0xbb800000, v113
	v_fmac_f32_e32 v98, 0xbb800000, v114
	v_fmac_f32_e32 v99, 0xbb800000, v114
	v_fmac_f32_e32 v57, 0xbb800000, v114
	s_waitcnt lgkmcnt(0)
	v_add_f32_e32 v115, v108, v104
	ds_bpermute_b32 v104, v208, v109
	v_mov_b32_e32 v108, v61
	v_mov_b32_e32 v61, v94
	v_mov_b32_e32 v94, v59
	v_mov_b32_e32 v59, v96
	s_waitcnt lgkmcnt(0)
	v_add_f32_e32 v116, v109, v104
	ds_bpermute_b32 v104, v208, v68
	v_mov_b32_e32 v109, v95
	v_mov_b32_e32 v95, v97
	v_fmac_f32_e32 v56, 0xbb800000, v114
	v_fmac_f32_e32 v100, 0xbb800000, v115
	s_waitcnt lgkmcnt(0)
	v_add_f32_e32 v117, v68, v104
	v_mov_b32_e32 v104, v65
	v_mov_b32_e32 v65, v70
	v_pk_mul_f32 v[68:69], v[104:105], v[104:105]
	v_pk_mul_f32 v[70:71], v[64:65], v[64:65]
	v_fmac_f32_e32 v101, 0xbb800000, v115
	v_pk_mov_b32 v[106:107], v[70:71], v[68:69] op_sel:[1,0]
	v_mov_b32_e32 v71, v69
	v_pk_add_f32 v[68:69], v[106:107], v[70:71]
	v_mov_b32_e32 v106, v63
	v_mov_b32_e32 v107, v73
	v_mov_b32_e32 v63, v72
	v_add_f32_e32 v118, v68, v69
	v_pk_mul_f32 v[68:69], v[106:107], v[106:107]
	v_pk_mul_f32 v[70:71], v[62:63], v[62:63]
	v_fmac_f32_e32 v55, 0xbb800000, v115
	v_pk_mov_b32 v[72:73], v[70:71], v[68:69] op_sel:[1,0]
	v_mov_b32_e32 v71, v69
	v_pk_add_f32 v[68:69], v[72:73], v[70:71]
	v_pk_mul_f32 v[70:71], v[60:61], v[60:61]
	v_add_f32_e32 v111, v68, v69
	v_pk_mul_f32 v[68:69], v[108:109], v[108:109]
	v_fmac_f32_e32 v54, 0xbb800000, v115
	v_pk_mov_b32 v[72:73], v[70:71], v[68:69] op_sel:[1,0]
	v_mov_b32_e32 v71, v69
	v_pk_add_f32 v[68:69], v[72:73], v[70:71]
	v_pk_mul_f32 v[70:71], v[58:59], v[58:59]
	v_add_f32_e32 v112, v68, v69
	v_pk_mul_f32 v[68:69], v[94:95], v[94:95]
	v_fmac_f32_e32 v66, 0xbb800000, v116
	v_pk_mov_b32 v[72:73], v[70:71], v[68:69] op_sel:[1,0]
	v_mov_b32_e32 v71, v69
	v_pk_add_f32 v[68:69], v[72:73], v[70:71]
	v_mov_b32_e32 v72, v57
	v_mov_b32_e32 v73, v99
	v_mov_b32_e32 v57, v98
	v_add_f32_e32 v113, v68, v69
	v_pk_mul_f32 v[68:69], v[72:73], v[72:73]
	v_pk_mul_f32 v[70:71], v[56:57], v[56:57]
	v_fmac_f32_e32 v67, 0xbb800000, v116
	v_pk_mov_b32 v[96:97], v[70:71], v[68:69] op_sel:[1,0]
	v_mov_b32_e32 v71, v69
	v_pk_add_f32 v[68:69], v[96:97], v[70:71]
	v_mov_b32_e32 v70, v55
	v_mov_b32_e32 v71, v101
	v_mov_b32_e32 v55, v100
	v_add_f32_e32 v114, v68, v69
	v_pk_mul_f32 v[68:69], v[70:71], v[70:71]
	v_pk_mul_f32 v[96:97], v[54:55], v[54:55]
	v_fmac_f32_e32 v53, 0xbb800000, v116
	v_pk_mov_b32 v[98:99], v[96:97], v[68:69] op_sel:[1,0]
	v_mov_b32_e32 v97, v69
	v_pk_add_f32 v[68:69], v[98:99], v[96:97]
	v_fmac_f32_e32 v52, 0xbb800000, v116
	v_add_f32_e32 v115, v68, v69
	v_mov_b32_e32 v68, v53
	v_mov_b32_e32 v69, v67
	v_mov_b32_e32 v53, v66
	v_pk_mul_f32 v[96:97], v[68:69], v[68:69]
	v_pk_mul_f32 v[66:67], v[52:53], v[52:53]
	v_fmac_f32_e32 v102, 0xbb800000, v117
	v_pk_mov_b32 v[98:99], v[66:67], v[96:97] op_sel:[1,0]
	v_mov_b32_e32 v67, v97
	v_pk_add_f32 v[66:67], v[98:99], v[66:67]
	v_fmac_f32_e32 v103, 0xbb800000, v117
	v_fmac_f32_e32 v51, 0xbb800000, v117
	v_add_f32_e32 v116, v66, v67
	v_fmac_f32_e32 v50, 0xbb800000, v117
	v_mov_b32_e32 v66, v51
	v_mov_b32_e32 v67, v103
	v_mov_b32_e32 v51, v102
	v_pk_mul_f32 v[96:97], v[66:67], v[66:67]
	v_pk_mul_f32 v[98:99], v[50:51], v[50:51]
	ds_bpermute_b32 v102, v213, v115
	v_pk_mov_b32 v[100:101], v[98:99], v[96:97] op_sel:[1,0]
	v_mov_b32_e32 v99, v97
	v_pk_add_f32 v[96:97], v[100:101], v[98:99]
	ds_bpermute_b32 v98, v213, v111
	v_add_f32_e32 v96, v96, v97
	ds_bpermute_b32 v97, v213, v118
	ds_bpermute_b32 v99, v213, v112
	ds_bpermute_b32 v100, v213, v113
	s_waitcnt lgkmcnt(3)
	v_add_f32_e32 v98, v111, v98
	ds_bpermute_b32 v111, v213, v96
	s_waitcnt lgkmcnt(3)
	v_add_f32_e32 v97, v118, v97
	s_waitcnt lgkmcnt(2)
	v_add_f32_e32 v99, v112, v99
	s_waitcnt lgkmcnt(1)
	v_add_f32_e32 v100, v113, v100
	ds_bpermute_b32 v101, v213, v114
	s_waitcnt lgkmcnt(1)
	v_add_f32_e32 v96, v96, v111
	ds_bpermute_b32 v111, v214, v97
	v_add_f32_e32 v102, v115, v102
	ds_bpermute_b32 v103, v213, v116
	s_waitcnt lgkmcnt(2)
	v_add_f32_e32 v101, v114, v101
	s_waitcnt lgkmcnt(1)
	v_add_f32_e32 v97, v97, v111
	ds_bpermute_b32 v111, v214, v98
	s_waitcnt lgkmcnt(1)
	v_add_f32_e32 v103, v116, v103
	s_waitcnt lgkmcnt(0)
	v_add_f32_e32 v98, v98, v111
	ds_bpermute_b32 v111, v214, v99
	s_waitcnt lgkmcnt(0)
	v_add_f32_e32 v99, v99, v111
	ds_bpermute_b32 v111, v214, v100
	s_waitcnt lgkmcnt(0)
	v_add_f32_e32 v100, v100, v111
	ds_bpermute_b32 v111, v214, v101
	s_waitcnt lgkmcnt(0)
	v_add_f32_e32 v101, v101, v111
	ds_bpermute_b32 v111, v214, v102
	s_waitcnt lgkmcnt(0)
; #define LAS __attribute__((address_space(3)))
; __device__ __forceinline__ unsigned pk2(float lo, float hi) { unsigned r; asm("v_cvt_pk_bf16_f32 %0, %1, %2" : "=v"(r) : "v"(lo), "v"(hi)); return r; }
; __device__ __forceinline__ float fast_rcp(float x) { return __builtin_amdgcn_rcpf(x); }
; __device__ __forceinline__ float fast_exp2(float x) { return __builtin_amdgcn_exp2f(x); }
; __device__ __forceinline__ float rsq(float x) { return __builtin_amdgcn_rsqf(x); }
; __device__ __forceinline__ float sigmoidf_(float x) { return fast_rcp(1.0f + fast_exp2(-1.4426950408889634f * x)); }
; __device__ __forceinline__ void mixer_chunk(KP p, LAS unsigned char* lds, int l, int chunk) {
;     ...
;                 for (int i = 0; i < 8; ++i) s[i] += __shfl_xor(s[i], o);
; #pragma unroll
;             for (int i = 0; i < 8; ++i) {
;                 const float rstd = rsq(s[i] * (1.0f / 256.0f) + EPS);
;                 f32x4 y = x[i] * rstd * lg + lb;
; #pragma unroll
;                 for (int j = 0; j < 4; ++j) y[j] = y[j] * sigmoidf_(y[j]);
;                 u32x2 o; o.x = pk2(y[0], y[1]); o.y = pk2(y[2], y[3]); *(LAS u32x2*)(CO + (16 * w + 8 * half + i) * YLD + 4 * lane) = o;
;             }
	v_add_f32_e32 v102, v102, v111
	ds_bpermute_b32 v111, v214, v103
	s_waitcnt lgkmcnt(0)
	v_add_f32_e32 v103, v103, v111
	ds_bpermute_b32 v111, v214, v96
	s_waitcnt lgkmcnt(0)
	v_add_f32_e32 v96, v96, v111
	ds_bpermute_b32 v111, v91, v97
	s_waitcnt lgkmcnt(0)
	v_add_f32_e32 v97, v97, v111
	ds_bpermute_b32 v111, v91, v98
	s_waitcnt lgkmcnt(0)
	v_add_f32_e32 v98, v98, v111
	ds_bpermute_b32 v111, v91, v99
	s_waitcnt lgkmcnt(0)
	v_add_f32_e32 v99, v99, v111
	ds_bpermute_b32 v111, v91, v100
	s_waitcnt lgkmcnt(0)
	v_add_f32_e32 v100, v100, v111
	ds_bpermute_b32 v111, v91, v101
	s_waitcnt lgkmcnt(0)
	v_add_f32_e32 v101, v101, v111
	ds_bpermute_b32 v111, v91, v102
	s_waitcnt lgkmcnt(0)
	v_add_f32_e32 v102, v102, v111
	ds_bpermute_b32 v111, v91, v103
	s_waitcnt lgkmcnt(0)
	v_add_f32_e32 v103, v103, v111
	ds_bpermute_b32 v111, v91, v96
	s_waitcnt lgkmcnt(0)
	v_add_f32_e32 v96, v96, v111
	ds_bpermute_b32 v111, v92, v97
	s_waitcnt lgkmcnt(0)
	v_add_f32_e32 v97, v97, v111
	ds_bpermute_b32 v111, v92, v98
	s_waitcnt lgkmcnt(0)
	v_add_f32_e32 v98, v98, v111
	ds_bpermute_b32 v111, v92, v99
	s_waitcnt lgkmcnt(0)
	v_add_f32_e32 v99, v99, v111
	ds_bpermute_b32 v111, v92, v100
	s_waitcnt lgkmcnt(0)
	v_add_f32_e32 v100, v100, v111
	ds_bpermute_b32 v111, v92, v101
	s_waitcnt lgkmcnt(0)
	v_add_f32_e32 v101, v101, v111
	ds_bpermute_b32 v111, v92, v102
	s_waitcnt lgkmcnt(0)
	v_add_f32_e32 v102, v102, v111
	ds_bpermute_b32 v111, v92, v103
	s_waitcnt lgkmcnt(0)
	v_add_f32_e32 v103, v103, v111
	ds_bpermute_b32 v111, v92, v96
	s_waitcnt lgkmcnt(0)
	v_add_f32_e32 v96, v96, v111
	ds_bpermute_b32 v111, v207, v97
	s_waitcnt lgkmcnt(0)
	v_add_f32_e32 v97, v97, v111
	ds_bpermute_b32 v111, v207, v98
	s_waitcnt lgkmcnt(0)
	v_add_f32_e32 v98, v98, v111
	ds_bpermute_b32 v111, v207, v99
	s_waitcnt lgkmcnt(0)
	v_add_f32_e32 v99, v99, v111
	ds_bpermute_b32 v111, v207, v100
	s_waitcnt lgkmcnt(0)
	v_add_f32_e32 v100, v100, v111
	ds_bpermute_b32 v111, v207, v101
	s_waitcnt lgkmcnt(0)
	v_add_f32_e32 v101, v101, v111
	ds_bpermute_b32 v111, v207, v102
	s_waitcnt lgkmcnt(0)
	v_add_f32_e32 v102, v102, v111
	ds_bpermute_b32 v111, v207, v103
	s_waitcnt lgkmcnt(0)
	v_add_f32_e32 v103, v103, v111
	ds_bpermute_b32 v111, v207, v96
	s_waitcnt lgkmcnt(0)
	v_add_f32_e32 v96, v96, v111
	ds_bpermute_b32 v111, v208, v97
	s_waitcnt lgkmcnt(0)
	v_add_f32_e32 v97, v97, v111
	ds_bpermute_b32 v111, v208, v98
	s_waitcnt lgkmcnt(0)
	v_add_f32_e32 v98, v98, v111
	ds_bpermute_b32 v111, v208, v99
	s_waitcnt lgkmcnt(0)
	v_add_f32_e32 v99, v99, v111
	ds_bpermute_b32 v111, v208, v100
	s_waitcnt lgkmcnt(0)
	v_add_f32_e32 v100, v100, v111
	ds_bpermute_b32 v111, v208, v101
	s_waitcnt lgkmcnt(0)
	v_add_f32_e32 v101, v101, v111
	ds_bpermute_b32 v111, v208, v102
	s_waitcnt lgkmcnt(0)
	v_add_f32_e32 v102, v102, v111
	ds_bpermute_b32 v111, v208, v103
	s_waitcnt lgkmcnt(0)
	v_add_f32_e32 v103, v103, v111
	ds_bpermute_b32 v111, v208, v96
	s_waitcnt lgkmcnt(0)
	v_add_f32_e32 v111, v96, v111
	v_fmamk_f32 v96, v97, 0x3b800000, v189
	v_rsq_f32_e32 v96, v96
	s_nop 0
	v_pk_mul_f32 v[64:65], v[64:65], v[96:97] op_sel_hi:[1,0]
	s_waitcnt vmcnt(1)
	v_pk_fma_f32 v[64:65], v[42:43], v[64:65], v[46:47]
	v_pk_mul_f32 v[96:97], v[104:105], v[96:97] op_sel_hi:[1,0]
	v_mul_f32_e32 v104, 0xbfb8aa3b, v64
	v_exp_f32_e32 v104, v104
	v_pk_fma_f32 v[96:97], v[44:45], v[96:97], v[48:49]
	v_add_f32_e32 v104, 1.0, v104
	v_rcp_f32_e32 v104, v104
	s_nop 0
	v_mul_f32_e32 v64, v64, v104
	v_mul_f32_e32 v104, 0xbfb8aa3b, v65
	v_exp_f32_e32 v104, v104
	s_nop 0
	v_add_f32_e32 v104, 1.0, v104
	v_rcp_f32_e32 v104, v104
	s_nop 0
	v_mul_f32_e32 v65, v65, v104
	v_mul_f32_e32 v104, 0xbfb8aa3b, v96
	v_exp_f32_e32 v104, v104
	v_cvt_pk_bf16_f32 v64, v64, v65
	s_nop 0
	v_add_f32_e32 v104, 1.0, v104
	v_rcp_f32_e32 v104, v104
	s_nop 0
	v_mul_f32_e32 v96, v96, v104
	v_mul_f32_e32 v104, 0xbfb8aa3b, v97
	v_exp_f32_e32 v104, v104
	s_nop 0
	v_add_f32_e32 v104, 1.0, v104
	v_rcp_f32_e32 v104, v104
	s_nop 0
	v_mul_f32_e32 v97, v97, v104
	v_cvt_pk_bf16_f32 v65, v96, v97
	v_fmamk_f32 v96, v98, 0x3b800000, v189
	v_rsq_f32_e32 v96, v96
	s_nop 0
	v_pk_mul_f32 v[62:63], v[62:63], v[96:97] op_sel_hi:[1,0]
	s_nop 0
	v_pk_fma_f32 v[62:63], v[42:43], v[62:63], v[46:47]
	v_pk_mul_f32 v[96:97], v[106:107], v[96:97] op_sel_hi:[1,0]
	v_mul_f32_e32 v98, 0xbfb8aa3b, v62
	v_exp_f32_e32 v98, v98
	v_pk_fma_f32 v[96:97], v[44:45], v[96:97], v[48:49]
	v_add_f32_e32 v98, 1.0, v98
	v_rcp_f32_e32 v98, v98
	s_nop 0
	v_mul_f32_e32 v62, v62, v98
	v_mul_f32_e32 v98, 0xbfb8aa3b, v63
	v_exp_f32_e32 v98, v98
	s_nop 0
	v_add_f32_e32 v98, 1.0, v98
	v_rcp_f32_e32 v98, v98
	s_nop 0
	v_mul_f32_e32 v63, v63, v98
	v_mul_f32_e32 v98, 0xbfb8aa3b, v96
	v_exp_f32_e32 v98, v98
	v_cvt_pk_bf16_f32 v62, v62, v63
	s_nop 0
	v_add_f32_e32 v98, 1.0, v98
	v_rcp_f32_e32 v98, v98
	s_nop 0
	v_mul_f32_e32 v96, v96, v98
	v_mul_f32_e32 v98, 0xbfb8aa3b, v97
	v_exp_f32_e32 v98, v98
	s_nop 0
	v_add_f32_e32 v98, 1.0, v98
	v_rcp_f32_e32 v98, v98
	s_nop 0
	v_mul_f32_e32 v97, v97, v98
	v_cvt_pk_bf16_f32 v63, v96, v97
	ds_write2_b64 v110, v[64:65], v[62:63] offset1:66
	v_fmamk_f32 v62, v99, 0x3b800000, v189
	v_rsq_f32_e32 v62, v62
	s_nop 0
	v_pk_mul_f32 v[60:61], v[60:61], v[62:63] op_sel_hi:[1,0]
	s_nop 0
	v_pk_fma_f32 v[60:61], v[42:43], v[60:61], v[46:47]
	v_pk_mul_f32 v[62:63], v[108:109], v[62:63] op_sel_hi:[1,0]
	v_mul_f32_e32 v64, 0xbfb8aa3b, v60
	v_exp_f32_e32 v64, v64
	v_pk_fma_f32 v[62:63], v[44:45], v[62:63], v[48:49]
	v_add_f32_e32 v64, 1.0, v64
	v_rcp_f32_e32 v64, v64
	s_nop 0
	v_mul_f32_e32 v60, v60, v64
	v_mul_f32_e32 v64, 0xbfb8aa3b, v61
	v_exp_f32_e32 v64, v64
	s_nop 0
	v_add_f32_e32 v64, 1.0, v64
	v_rcp_f32_e32 v64, v64
; #define LAS __attribute__((address_space(3)))
; __device__ __forceinline__ unsigned pk2(float lo, float hi) { unsigned r; asm("v_cvt_pk_bf16_f32 %0, %1, %2" : "=v"(r) : "v"(lo), "v"(hi)); return r; }
; __device__ __forceinline__ float sigmoidf_(float x) { return fast_rcp(1.0f + fast_exp2(-1.4426950408889634f * x)); }
; __device__ __forceinline__ float rsq(float x) { return __builtin_amdgcn_rsqf(x); }
; __device__ __forceinline__ void mixer_chunk(KP p, LAS unsigned char* lds, int l, int chunk) {
;     ...
;             for (int i = 0; i < 8; ++i) {
;                 const float rstd = rsq(s[i] * (1.0f / 256.0f) + EPS);
;                 f32x4 y = x[i] * rstd * lg + lb;
; #pragma unroll
;                 for (int j = 0; j < 4; ++j) y[j] = y[j] * sigmoidf_(y[j]);
;                 u32x2 o; o.x = pk2(y[0], y[1]); o.y = pk2(y[2], y[3]); *(LAS u32x2*)(CO + (16 * w + 8 * half + i) * YLD + 4 * lane) = o;
;             }
	s_nop 0
	v_mul_f32_e32 v61, v61, v64
	v_mul_f32_e32 v64, 0xbfb8aa3b, v62
	v_exp_f32_e32 v64, v64
	v_cvt_pk_bf16_f32 v60, v60, v61
	s_nop 0
	v_add_f32_e32 v64, 1.0, v64
	v_rcp_f32_e32 v64, v64
	s_nop 0
	v_mul_f32_e32 v62, v62, v64
	v_mul_f32_e32 v64, 0xbfb8aa3b, v63
	v_exp_f32_e32 v64, v64
	s_nop 0
	v_add_f32_e32 v64, 1.0, v64
	v_rcp_f32_e32 v64, v64
	s_nop 0
	v_mul_f32_e32 v63, v63, v64
	v_cvt_pk_bf16_f32 v61, v62, v63
	v_fmamk_f32 v62, v100, 0x3b800000, v189
	v_rsq_f32_e32 v62, v62
	s_nop 0
	v_pk_mul_f32 v[58:59], v[58:59], v[62:63] op_sel_hi:[1,0]
	s_nop 0
	v_pk_fma_f32 v[58:59], v[42:43], v[58:59], v[46:47]
	v_pk_mul_f32 v[62:63], v[94:95], v[62:63] op_sel_hi:[1,0]
	v_mul_f32_e32 v64, 0xbfb8aa3b, v58
	v_exp_f32_e32 v64, v64
	v_pk_fma_f32 v[62:63], v[44:45], v[62:63], v[48:49]
	v_add_f32_e32 v64, 1.0, v64
	v_rcp_f32_e32 v64, v64
	s_nop 0
	v_mul_f32_e32 v58, v58, v64
	v_mul_f32_e32 v64, 0xbfb8aa3b, v59
	v_exp_f32_e32 v64, v64
	s_nop 0
	v_add_f32_e32 v64, 1.0, v64
	v_rcp_f32_e32 v64, v64
	s_nop 0
	v_mul_f32_e32 v59, v59, v64
	v_mul_f32_e32 v64, 0xbfb8aa3b, v62
	v_exp_f32_e32 v64, v64
	v_cvt_pk_bf16_f32 v58, v58, v59
	s_nop 0
	v_add_f32_e32 v64, 1.0, v64
	v_rcp_f32_e32 v64, v64
	s_nop 0
	v_mul_f32_e32 v62, v62, v64
	v_mul_f32_e32 v64, 0xbfb8aa3b, v63
	v_exp_f32_e32 v64, v64
	s_nop 0
	v_add_f32_e32 v64, 1.0, v64
	v_rcp_f32_e32 v64, v64
	s_nop 0
	v_mul_f32_e32 v63, v63, v64
	v_cvt_pk_bf16_f32 v59, v62, v63
	ds_write2_b64 v110, v[60:61], v[58:59] offset0:132 offset1:198
	v_fmamk_f32 v58, v101, 0x3b800000, v189
	v_rsq_f32_e32 v58, v58
	s_nop 0
	v_pk_mul_f32 v[56:57], v[56:57], v[58:59] op_sel_hi:[1,0]
	s_nop 0
	v_pk_fma_f32 v[56:57], v[42:43], v[56:57], v[46:47]
	v_pk_mul_f32 v[58:59], v[72:73], v[58:59] op_sel_hi:[1,0]
	v_mul_f32_e32 v60, 0xbfb8aa3b, v56
	v_exp_f32_e32 v60, v60
	v_pk_fma_f32 v[58:59], v[44:45], v[58:59], v[48:49]
	v_add_f32_e32 v60, 1.0, v60
	v_rcp_f32_e32 v60, v60
	s_nop 0
	v_mul_f32_e32 v56, v56, v60
	v_mul_f32_e32 v60, 0xbfb8aa3b, v57
	v_exp_f32_e32 v60, v60
	s_nop 0
	v_add_f32_e32 v60, 1.0, v60
	v_rcp_f32_e32 v60, v60
	s_nop 0
	v_mul_f32_e32 v57, v57, v60
	v_mul_f32_e32 v60, 0xbfb8aa3b, v58
	v_exp_f32_e32 v60, v60
	v_cvt_pk_bf16_f32 v56, v56, v57
	s_nop 0
	v_add_f32_e32 v60, 1.0, v60
	v_rcp_f32_e32 v60, v60
	s_nop 0
	v_mul_f32_e32 v58, v58, v60
	v_mul_f32_e32 v60, 0xbfb8aa3b, v59
	v_exp_f32_e32 v60, v60
	s_nop 0
	v_add_f32_e32 v60, 1.0, v60
	v_rcp_f32_e32 v60, v60
	s_nop 0
	v_mul_f32_e32 v59, v59, v60
	v_cvt_pk_bf16_f32 v57, v58, v59
	v_fmamk_f32 v58, v102, 0x3b800000, v189
	v_rsq_f32_e32 v58, v58
	s_nop 0
	v_pk_mul_f32 v[54:55], v[54:55], v[58:59] op_sel_hi:[1,0]
	s_nop 0
	v_pk_fma_f32 v[54:55], v[42:43], v[54:55], v[46:47]
	v_pk_mul_f32 v[58:59], v[70:71], v[58:59] op_sel_hi:[1,0]
	v_mul_f32_e32 v60, 0xbfb8aa3b, v54
	v_exp_f32_e32 v60, v60
	v_pk_fma_f32 v[58:59], v[44:45], v[58:59], v[48:49]
	v_add_f32_e32 v60, 1.0, v60
	v_rcp_f32_e32 v60, v60
	s_nop 0
	v_mul_f32_e32 v54, v54, v60
	v_mul_f32_e32 v60, 0xbfb8aa3b, v55
	v_exp_f32_e32 v60, v60
	s_nop 0
	v_add_f32_e32 v60, 1.0, v60
	v_rcp_f32_e32 v60, v60
	s_nop 0
	v_mul_f32_e32 v55, v55, v60
	v_mul_f32_e32 v60, 0xbfb8aa3b, v58
	v_exp_f32_e32 v60, v60
	v_cvt_pk_bf16_f32 v54, v54, v55
	s_nop 0
	v_add_f32_e32 v60, 1.0, v60
	v_rcp_f32_e32 v60, v60
	s_nop 0
	v_mul_f32_e32 v58, v58, v60
	v_mul_f32_e32 v60, 0xbfb8aa3b, v59
	v_exp_f32_e32 v60, v60
	s_nop 0
	v_add_f32_e32 v60, 1.0, v60
	v_rcp_f32_e32 v60, v60
	s_nop 0
	v_mul_f32_e32 v59, v59, v60
	v_cvt_pk_bf16_f32 v55, v58, v59
	ds_write2_b64 v93, v[56:57], v[54:55] offset0:8 offset1:74
	v_fmamk_f32 v54, v103, 0x3b800000, v189
	v_rsq_f32_e32 v54, v54
	s_nop 0
	v_pk_mul_f32 v[52:53], v[52:53], v[54:55] op_sel_hi:[1,0]
	s_nop 0
	v_pk_fma_f32 v[52:53], v[42:43], v[52:53], v[46:47]
	v_pk_mul_f32 v[54:55], v[68:69], v[54:55] op_sel_hi:[1,0]
	v_mul_f32_e32 v56, 0xbfb8aa3b, v52
	v_exp_f32_e32 v56, v56
	v_pk_fma_f32 v[54:55], v[44:45], v[54:55], v[48:49]
	v_add_f32_e32 v56, 1.0, v56
	v_rcp_f32_e32 v56, v56
	s_nop 0
	v_mul_f32_e32 v52, v52, v56
	v_mul_f32_e32 v56, 0xbfb8aa3b, v53
	v_exp_f32_e32 v56, v56
	s_nop 0
	v_add_f32_e32 v56, 1.0, v56
	v_rcp_f32_e32 v56, v56
	s_nop 0
	v_mul_f32_e32 v53, v53, v56
	v_mul_f32_e32 v56, 0xbfb8aa3b, v54
	v_exp_f32_e32 v56, v56
	v_cvt_pk_bf16_f32 v52, v52, v53
	s_nop 0
	v_add_f32_e32 v56, 1.0, v56
	v_rcp_f32_e32 v56, v56
	s_nop 0
	v_mul_f32_e32 v54, v54, v56
	v_mul_f32_e32 v56, 0xbfb8aa3b, v55
	v_exp_f32_e32 v56, v56
	s_nop 0
	v_add_f32_e32 v56, 1.0, v56
	v_rcp_f32_e32 v56, v56
	s_nop 0
	v_mul_f32_e32 v55, v55, v56
	v_cvt_pk_bf16_f32 v53, v54, v55
	v_fmamk_f32 v54, v111, 0x3b800000, v189
	v_rsq_f32_e32 v54, v54
	s_nop 0
	v_pk_mul_f32 v[50:51], v[50:51], v[54:55] op_sel_hi:[1,0]
	s_nop 0
	v_pk_fma_f32 v[50:51], v[42:43], v[50:51], v[46:47]
	v_pk_mul_f32 v[54:55], v[66:67], v[54:55] op_sel_hi:[1,0]
	v_mul_f32_e32 v56, 0xbfb8aa3b, v50
	v_exp_f32_e32 v56, v56
	v_pk_fma_f32 v[54:55], v[44:45], v[54:55], v[48:49]
	v_add_f32_e32 v56, 1.0, v56
	v_rcp_f32_e32 v56, v56
	s_nop 0
	v_mul_f32_e32 v50, v50, v56
	v_mul_f32_e32 v56, 0xbfb8aa3b, v51
	v_exp_f32_e32 v56, v56
	s_nop 0
	v_add_f32_e32 v56, 1.0, v56
	v_rcp_f32_e32 v56, v56
	s_nop 0
	v_mul_f32_e32 v51, v51, v56
	v_mul_f32_e32 v56, 0xbfb8aa3b, v54
	v_exp_f32_e32 v56, v56
	v_cvt_pk_bf16_f32 v50, v50, v51
	s_nop 0
	v_add_f32_e32 v56, 1.0, v56
	v_rcp_f32_e32 v56, v56
	s_nop 0
	v_mul_f32_e32 v54, v54, v56
	v_mul_f32_e32 v56, 0xbfb8aa3b, v55
	v_exp_f32_e32 v56, v56
	s_nop 0
	v_add_f32_e32 v56, 1.0, v56
	v_rcp_f32_e32 v56, v56
	s_nop 0
	v_mul_f32_e32 v55, v55, v56
	v_cvt_pk_bf16_f32 v51, v54, v55
	ds_write2_b64 v93, v[52:53], v[50:51] offset0:140 offset1:206
	s_cbranch_vccz .LBB0_297
; #define LAS __attribute__((address_space(3)))
; __device__ __forceinline__ f32x4 mfma16(bf16x8 a, bf16x8 b, f32x4 c) { return __builtin_amdgcn_mfma_f32_16x16x32_bf16(a, b, c, 0, 0, 0); }
; template <int NKS, int NNT>
; __device__ __forceinline__ void wgemm(f32x4 (&acc)[8][NNT], const LAS bf16_t* A, const int lda, const bf16_t* Bp, const int ldb) {
;     u32x4 bf[NNT][NKS];
; #pragma unroll
;     for (int nt = 0; nt < NNT; ++nt) ldfr(bf[nt], Bp + (size_t)(16 * nt) * ldb);
; #pragma unroll
;     for (int nt = 0; nt < NNT; ++nt) pin(bf[nt]);
; #pragma unroll
;     for (int mt = 0; mt < 8; ++mt) {
;         bf16x8 af[NKS];
; #pragma unroll
;         for (int ks = 0; ks < NKS; ++ks) af[ks] = *(const LAS bf16x8*)(A + (16 * mt) * lda + 32 * ks);
; #pragma unroll
;         for (int nt = 0; nt < NNT; ++nt) { f32x4 a = (f32x4){0.f, 0.f, 0.f, 0.f};
; #pragma unroll
;             for (int ks = 0; ks < NKS; ++ks) a = mfma16(as_bf16x8(bf[nt][ks]), af[ks], a);
;             acc[mt][nt] = a; }
;     }
; }
; __device__ __forceinline__ void mixer_chunk(KP p, LAS unsigned char* lds, int l, int chunk) {
;     ...
;     pin(sq); pin(sk);
; #pragma unroll
;     for (int i = 0; i < 6; ++i) { const int q = tid + 512 * i, r = q / 24, pc = q % 24; *(LAS u32x4*)(CQ + r * CQLD + 8 * pc) = sq[i]; }
; #pragma unroll
;     for (int i = 0; i < 4; ++i) { const int q = tid + 512 * i, r = q >> 4, pc = q & 15; *(LAS u32x4*)(CK + r * CKLD + 8 * pc) = sk[i]; }
;     __syncthreads();
;     f32x4 accc[8][2];
;     wgemm<8, 2>(accc, CO + fr * YLD + 8 * fq, YLD, (const bf16_t*)(ws + OFF_PW + l * SZ_PW) + (size_t)(32 * w + fr) * 256 + 8 * fq, 256);
	s_movk_i32 s6, 0x190
	v_mul_lo_u32 v0, v74, s6
	v_lshlrev_b32_e32 v42, 4, v75
	v_add3_u32 v0, 0, v0, v42
	ds_write_b128 v0, v[2:5]
	v_mul_lo_u32 v0, v76, s6
	v_lshlrev_b32_e32 v2, 4, v77
	v_add3_u32 v0, 0, v0, v2
	ds_write_b128 v0, v[6:9]
	v_mul_lo_u32 v0, v78, s6
	v_lshlrev_b32_e32 v2, 4, v79
	v_add3_u32 v0, 0, v0, v2
	ds_write_b128 v0, v[10:13]
	v_mul_lo_u32 v0, v80, s6
	v_lshlrev_b32_e32 v2, 4, v81
	v_add3_u32 v0, 0, v0, v2
	ds_write_b128 v0, v[14:17]
	v_mul_lo_u32 v0, v82, s6
	v_lshlrev_b32_e32 v2, 4, v83
	v_add3_u32 v0, 0, v0, v2
	ds_write_b128 v0, v[18:21]
	v_mul_lo_u32 v0, v84, s6
	v_lshlrev_b32_e32 v2, 4, v85
	v_add3_u32 v0, 0, v0, v2
	ds_write_b128 v0, v[22:25]
	v_lshl_add_u32 v0, v87, 1, 0
	v_mad_u64_u32 v[2:3], s[6:7], v86, s64, v[0:1]
	ds_write_b128 v2, v[26:29] offset:51200
	v_mad_u64_u32 v[2:3], s[6:7], v88, s64, v[0:1]
	ds_write_b128 v2, v[30:33] offset:51200
	v_mad_u64_u32 v[2:3], s[6:7], v89, s64, v[0:1]
	v_and_b32_e32 v217, 15, v204
	ds_write_b128 v2, v[34:37] offset:51200
	v_mad_u64_u32 v[2:3], s[6:7], v90, s64, v[0:1]
	s_lshl_b32 s42, s55, 5
	ds_write_b128 v2, v[38:41] offset:51200
	v_or_b32_e32 v2, s42, v217
	v_ashrrev_i32_e32 v3, 31, v2
	v_readlane_b32 s6, v252, 8
	v_lshlrev_b64 v[2:3], 9, v[2:3]
	v_readlane_b32 s7, v252, 9
	v_and_b32_e32 v0, 48, v205
	s_waitcnt lgkmcnt(0)
	v_lshl_add_u64 v[2:3], s[6:7], 0, v[2:3]
	v_lshl_add_u64 v[6:7], v[2:3], 0, v[0:1]
	s_barrier
	global_load_dwordx4 v[118:121], v[6:7], off
	global_load_dwordx4 v[114:117], v[6:7], off offset:64
	global_load_dwordx4 v[110:113], v[6:7], off offset:128
	global_load_dwordx4 v[106:109], v[6:7], off offset:192
	global_load_dwordx4 v[102:105], v[6:7], off offset:256
	global_load_dwordx4 v[90:93], v[6:7], off offset:320
	global_load_dwordx4 v[86:89], v[6:7], off offset:384
	global_load_dwordx4 v[2:5], v[6:7], off offset:448
	v_add_co_u32_e32 v6, vcc, s39, v6
	v_mov_b32_e32 v10, s69
	s_nop 0
	v_addc_co_u32_e32 v7, vcc, 0, v7, vcc
	global_load_dwordx4 v[94:97], v[6:7], off
	global_load_dwordx4 v[98:101], v[6:7], off offset:64
	global_load_dwordx4 v[82:85], v[6:7], off offset:128
	global_load_dwordx4 v[78:81], v[6:7], off offset:192
	global_load_dwordx4 v[74:77], v[6:7], off offset:256
	global_load_dwordx4 v[70:73], v[6:7], off offset:320
	global_load_dwordx4 v[66:69], v[6:7], off offset:384
	s_nop 0
	global_load_dwordx4 v[6:9], v[6:7], off offset:448
	v_mad_u32_u24 v219, v217, s67, v10
	v_add_u32_e32 v0, v219, v0
	v_lshlrev_b32_e32 v220, 5, v217
	v_readlane_b32 s6, v254, 20
	s_movk_i32 s18, 0x190
	v_cmp_gt_u32_e64 s[40:41], 16, v205
	v_add_u32_e32 v215, s6, v220
	v_lshl_add_u32 v216, s55, 2, v215
	s_waitcnt vmcnt(8)
	s_waitcnt vmcnt(0)
	ds_read_b128 v[10:13], v0
	ds_read_b128 v[14:17], v0 offset:64
	ds_read_b128 v[22:25], v0 offset:8448
	ds_read_b128 v[26:29], v0 offset:8512
	s_waitcnt lgkmcnt(3)
	v_mfma_f32_16x16x32_bf16 v[18:21], v[118:121], v[10:13], 0
	v_mfma_f32_16x16x32_bf16 v[10:13], v[94:97], v[10:13], 0
	s_waitcnt lgkmcnt(1)
	v_mfma_f32_16x16x32_bf16 v[30:33], v[118:121], v[22:25], 0
	v_mfma_f32_16x16x32_bf16 v[22:25], v[94:97], v[22:25], 0
	v_mfma_f32_16x16x32_bf16 v[18:21], v[114:117], v[14:17], v[18:21]
	v_mfma_f32_16x16x32_bf16 v[10:13], v[98:101], v[14:17], v[10:13]
	s_waitcnt lgkmcnt(0)
	v_mfma_f32_16x16x32_bf16 v[14:17], v[114:117], v[26:29], v[30:33]
	v_mfma_f32_16x16x32_bf16 v[22:25], v[98:101], v[26:29], v[22:25]
	ds_read_b128 v[26:29], v0 offset:128
	s_nop 0
	ds_read_b128 v[30:33], v0 offset:192
	s_waitcnt lgkmcnt(1)
	v_mfma_f32_16x16x32_bf16 v[18:21], v[110:113], v[26:29], v[18:21]
	v_mfma_f32_16x16x32_bf16 v[10:13], v[82:85], v[26:29], v[10:13]
	ds_read_b128 v[26:29], v0 offset:8576
	ds_read_b128 v[34:37], v0 offset:8640
	s_waitcnt lgkmcnt(1)
	v_mfma_f32_16x16x32_bf16 v[14:17], v[110:113], v[26:29], v[14:17]
	v_mfma_f32_16x16x32_bf16 v[22:25], v[82:85], v[26:29], v[22:25]
	v_mfma_f32_16x16x32_bf16 v[18:21], v[106:109], v[30:33], v[18:21]
	v_mfma_f32_16x16x32_bf16 v[10:13], v[78:81], v[30:33], v[10:13]
	ds_read_b128 v[26:29], v0 offset:256
	ds_read_b128 v[30:33], v0 offset:320
	s_waitcnt lgkmcnt(2)
	v_mfma_f32_16x16x32_bf16 v[14:17], v[106:109], v[34:37], v[14:17]
	v_mfma_f32_16x16x32_bf16 v[22:25], v[78:81], v[34:37], v[22:25]
	s_waitcnt lgkmcnt(1)
	v_mfma_f32_16x16x32_bf16 v[18:21], v[102:105], v[26:29], v[18:21]
	v_mfma_f32_16x16x32_bf16 v[10:13], v[74:77], v[26:29], v[10:13]
	ds_read_b128 v[26:29], v0 offset:8704
	ds_read_b128 v[34:37], v0 offset:8768
	s_waitcnt lgkmcnt(1)
	v_mfma_f32_16x16x32_bf16 v[14:17], v[102:105], v[26:29], v[14:17]
	v_mfma_f32_16x16x32_bf16 v[22:25], v[74:77], v[26:29], v[22:25]
	v_mfma_f32_16x16x32_bf16 v[18:21], v[90:93], v[30:33], v[18:21]
	v_mfma_f32_16x16x32_bf16 v[10:13], v[70:73], v[30:33], v[10:13]
	ds_read_b128 v[26:29], v0 offset:384
	ds_read_b128 v[30:33], v0 offset:448
	s_waitcnt lgkmcnt(2)
	v_mfma_f32_16x16x32_bf16 v[14:17], v[90:93], v[34:37], v[14:17]
	s_waitcnt lgkmcnt(1)
	v_mfma_f32_16x16x32_bf16 v[18:21], v[86:89], v[26:29], v[18:21]
	v_mfma_f32_16x16x32_bf16 v[10:13], v[66:69], v[26:29], v[10:13]
	ds_read_b128 v[26:29], v0 offset:8832
	ds_read_b128 v[38:41], v0 offset:8896
	v_mfma_f32_16x16x32_bf16 v[22:25], v[70:73], v[34:37], v[22:25]
	s_waitcnt lgkmcnt(1)
	v_mfma_f32_16x16x32_bf16 v[14:17], v[86:89], v[26:29], v[14:17]
	v_mfma_f32_16x16x32_bf16 v[58:61], v[6:9], v[30:33], v[10:13]
	v_mfma_f32_16x16x32_bf16 v[10:13], v[66:69], v[26:29], v[22:25]
	s_waitcnt lgkmcnt(0)
; #define LAS __attribute__((address_space(3)))
; __device__ __forceinline__ f32x4 mfma16(bf16x8 a, bf16x8 b, f32x4 c) { return __builtin_amdgcn_mfma_f32_16x16x32_bf16(a, b, c, 0, 0, 0); }
; template <int NKS, int NNT>
; __device__ __forceinline__ void wgemm(f32x4 (&acc)[8][NNT], const LAS bf16_t* A, const int lda, const bf16_t* Bp, const int ldb) {
;     u32x4 bf[NNT][NKS];
; #pragma unroll
;     for (int nt = 0; nt < NNT; ++nt) ldfr(bf[nt], Bp + (size_t)(16 * nt) * ldb);
; #pragma unroll
;     for (int nt = 0; nt < NNT; ++nt) pin(bf[nt]);
; #pragma unroll
;     for (int mt = 0; mt < 8; ++mt) {
;         bf16x8 af[NKS];
; #pragma unroll
;         for (int ks = 0; ks < NKS; ++ks) af[ks] = *(const LAS bf16x8*)(A + (16 * mt) * lda + 32 * ks);
; #pragma unroll
;         for (int nt = 0; nt < NNT; ++nt) { f32x4 a = (f32x4){0.f, 0.f, 0.f, 0.f};
; #pragma unroll
;             for (int ks = 0; ks < NKS; ++ks) a = mfma16(as_bf16x8(bf[nt][ks]), af[ks], a);
;             acc[mt][nt] = a; }
;     }
; }
	v_mfma_f32_16x16x32_bf16 v[54:57], v[2:5], v[38:41], v[14:17]
	v_mfma_f32_16x16x32_bf16 v[50:53], v[6:9], v[38:41], v[10:13]
	s_nop 4
	ds_read_b128 v[10:13], v0 offset:16896
	ds_read_b128 v[14:17], v0 offset:16960
	ds_read_b128 v[22:25], v0 offset:17024
	ds_read_b128 v[26:29], v0 offset:17088
	v_mfma_f32_16x16x32_bf16 v[62:65], v[2:5], v[30:33], v[18:21]
	ds_read_b128 v[30:33], v0 offset:17152
	ds_read_b128 v[34:37], v0 offset:17216
	ds_read_b128 v[38:41], v0 offset:17280
	ds_read_b128 v[42:45], v0 offset:17344
	s_waitcnt lgkmcnt(7)
	v_mfma_f32_16x16x32_bf16 v[18:21], v[118:121], v[10:13], 0
	v_mfma_f32_16x16x32_bf16 v[10:13], v[94:97], v[10:13], 0
	s_waitcnt lgkmcnt(6)
	v_mfma_f32_16x16x32_bf16 v[18:21], v[114:117], v[14:17], v[18:21]
	v_mfma_f32_16x16x32_bf16 v[10:13], v[98:101], v[14:17], v[10:13]
	s_waitcnt lgkmcnt(5)
	v_mfma_f32_16x16x32_bf16 v[18:21], v[110:113], v[22:25], v[18:21]
	v_mfma_f32_16x16x32_bf16 v[10:13], v[82:85], v[22:25], v[10:13]
	s_waitcnt lgkmcnt(4)
	v_mfma_f32_16x16x32_bf16 v[18:21], v[106:109], v[26:29], v[18:21]
	v_mfma_f32_16x16x32_bf16 v[10:13], v[78:81], v[26:29], v[10:13]
	s_waitcnt lgkmcnt(3)
	v_mfma_f32_16x16x32_bf16 v[18:21], v[102:105], v[30:33], v[18:21]
	v_mfma_f32_16x16x32_bf16 v[10:13], v[74:77], v[30:33], v[10:13]
	s_waitcnt lgkmcnt(2)
	v_mfma_f32_16x16x32_bf16 v[18:21], v[90:93], v[34:37], v[18:21]
	v_mfma_f32_16x16x32_bf16 v[10:13], v[70:73], v[34:37], v[10:13]
	s_waitcnt lgkmcnt(1)
	v_mfma_f32_16x16x32_bf16 v[18:21], v[86:89], v[38:41], v[18:21]
	v_mfma_f32_16x16x32_bf16 v[10:13], v[66:69], v[38:41], v[10:13]
	s_waitcnt lgkmcnt(0)
	v_mfma_f32_16x16x32_bf16 v[46:49], v[2:5], v[42:45], v[18:21]
	v_mfma_f32_16x16x32_bf16 v[42:45], v[6:9], v[42:45], v[10:13]
	s_nop 4
	ds_read_b128 v[10:13], v0 offset:25344
	ds_read_b128 v[14:17], v0 offset:25408
	ds_read_b128 v[22:25], v0 offset:25472
	ds_read_b128 v[26:29], v0 offset:25536
	ds_read_b128 v[30:33], v0 offset:25600
	ds_read_b128 v[34:37], v0 offset:25664
	s_waitcnt lgkmcnt(5)
	v_mfma_f32_16x16x32_bf16 v[18:21], v[118:121], v[10:13], 0
	ds_read_b128 v[122:125], v0 offset:25728
	ds_read_b128 v[126:129], v0 offset:25792
	v_mfma_f32_16x16x32_bf16 v[10:13], v[94:97], v[10:13], 0
	s_waitcnt lgkmcnt(6)
	v_mfma_f32_16x16x32_bf16 v[10:13], v[98:101], v[14:17], v[10:13]
	v_mfma_f32_16x16x32_bf16 v[18:21], v[114:117], v[14:17], v[18:21]
	s_waitcnt lgkmcnt(5)
	v_mfma_f32_16x16x32_bf16 v[10:13], v[82:85], v[22:25], v[10:13]
	v_mfma_f32_16x16x32_bf16 v[18:21], v[110:113], v[22:25], v[18:21]
	s_waitcnt lgkmcnt(4)
	v_mfma_f32_16x16x32_bf16 v[10:13], v[78:81], v[26:29], v[10:13]
	v_mfma_f32_16x16x32_bf16 v[18:21], v[106:109], v[26:29], v[18:21]
	s_waitcnt lgkmcnt(3)
	v_mfma_f32_16x16x32_bf16 v[10:13], v[74:77], v[30:33], v[10:13]
	v_mfma_f32_16x16x32_bf16 v[18:21], v[102:105], v[30:33], v[18:21]
	s_waitcnt lgkmcnt(2)
	v_mfma_f32_16x16x32_bf16 v[10:13], v[70:73], v[34:37], v[10:13]
	v_mfma_f32_16x16x32_bf16 v[18:21], v[90:93], v[34:37], v[18:21]
	s_waitcnt lgkmcnt(1)
	v_mfma_f32_16x16x32_bf16 v[10:13], v[66:69], v[122:125], v[10:13]
	v_mfma_f32_16x16x32_bf16 v[18:21], v[86:89], v[122:125], v[18:21]
	s_waitcnt lgkmcnt(0)
	v_mfma_f32_16x16x32_bf16 v[34:37], v[6:9], v[126:129], v[10:13]
	s_nop 4
	ds_read_b128 v[10:13], v0 offset:33792
	ds_read_b128 v[14:17], v0 offset:33856
	ds_read_b128 v[22:25], v0 offset:33920
	ds_read_b128 v[26:29], v0 offset:33984
	v_mfma_f32_16x16x32_bf16 v[38:41], v[2:5], v[126:129], v[18:21]
	ds_read_b128 v[122:125], v0 offset:34048
	ds_read_b128 v[126:129], v0 offset:34112
	ds_read_b128 v[130:133], v0 offset:34176
	ds_read_b128 v[134:137], v0 offset:34240
	s_waitcnt lgkmcnt(7)
	v_mfma_f32_16x16x32_bf16 v[18:21], v[118:121], v[10:13], 0
	v_mfma_f32_16x16x32_bf16 v[10:13], v[94:97], v[10:13], 0
	s_waitcnt lgkmcnt(6)
	v_mfma_f32_16x16x32_bf16 v[10:13], v[98:101], v[14:17], v[10:13]
	v_mfma_f32_16x16x32_bf16 v[18:21], v[114:117], v[14:17], v[18:21]
	s_waitcnt lgkmcnt(5)
	v_mfma_f32_16x16x32_bf16 v[10:13], v[82:85], v[22:25], v[10:13]
	v_mfma_f32_16x16x32_bf16 v[18:21], v[110:113], v[22:25], v[18:21]
	s_waitcnt lgkmcnt(4)
	v_mfma_f32_16x16x32_bf16 v[10:13], v[78:81], v[26:29], v[10:13]
	v_mfma_f32_16x16x32_bf16 v[18:21], v[106:109], v[26:29], v[18:21]
	s_waitcnt lgkmcnt(3)
	v_mfma_f32_16x16x32_bf16 v[10:13], v[74:77], v[122:125], v[10:13]
	v_mfma_f32_16x16x32_bf16 v[18:21], v[102:105], v[122:125], v[18:21]
	s_waitcnt lgkmcnt(2)
	v_mfma_f32_16x16x32_bf16 v[10:13], v[70:73], v[126:129], v[10:13]
	v_mfma_f32_16x16x32_bf16 v[18:21], v[90:93], v[126:129], v[18:21]
	s_waitcnt lgkmcnt(1)
	v_mfma_f32_16x16x32_bf16 v[10:13], v[66:69], v[130:133], v[10:13]
	v_mfma_f32_16x16x32_bf16 v[18:21], v[86:89], v[130:133], v[18:21]
	s_waitcnt lgkmcnt(0)
	v_mfma_f32_16x16x32_bf16 v[26:29], v[6:9], v[134:137], v[10:13]
	s_nop 4
	ds_read_b128 v[10:13], v0 offset:42240
	ds_read_b128 v[14:17], v0 offset:42304
	ds_read_b128 v[122:125], v0 offset:42368
	ds_read_b128 v[126:129], v0 offset:42432
	v_mfma_f32_16x16x32_bf16 v[30:33], v[2:5], v[134:137], v[18:21]
	ds_read_b128 v[130:133], v0 offset:42496
	ds_read_b128 v[134:137], v0 offset:42560
	ds_read_b128 v[138:141], v0 offset:42624
	ds_read_b128 v[142:145], v0 offset:42688
	s_waitcnt lgkmcnt(7)
; #define LAS __attribute__((address_space(3)))
; __device__ __forceinline__ f32x4 mfma16(bf16x8 a, bf16x8 b, f32x4 c) { return __builtin_amdgcn_mfma_f32_16x16x32_bf16(a, b, c, 0, 0, 0); }
; template <int NKS, int NNT>
; __device__ __forceinline__ void wgemm(f32x4 (&acc)[8][NNT], const LAS bf16_t* A, const int lda, const bf16_t* Bp, const int ldb) {
;     ...
;     for (int mt = 0; mt < 8; ++mt) {
;         bf16x8 af[NKS];
; #pragma unroll
;         for (int ks = 0; ks < NKS; ++ks) af[ks] = *(const LAS bf16x8*)(A + (16 * mt) * lda + 32 * ks);
; #pragma unroll
;         for (int nt = 0; nt < NNT; ++nt) { f32x4 a = (f32x4){0.f, 0.f, 0.f, 0.f};
; #pragma unroll
;             for (int ks = 0; ks < NKS; ++ks) a = mfma16(as_bf16x8(bf[nt][ks]), af[ks], a);
;             acc[mt][nt] = a; }
; template <int NNT>
; __device__ __forceinline__ void part_sumsq(const f32x4 (&acc)[8][NNT], LAS float* part, int w, int fr, int fq) {
; #pragma unroll
;     for (int mt = 0; mt < 8; ++mt) { float s = 0.f;
; #pragma unroll
;         for (int nt = 0; nt < NNT; ++nt) s += (acc[mt][nt][0] * acc[mt][nt][0] + acc[mt][nt][1] * acc[mt][nt][1]) + (acc[mt][nt][2] * acc[mt][nt][2] + acc[mt][nt][3] * acc[mt][nt][3]);
;         s += __shfl_xor(s, 16); s += __shfl_xor(s, 32);
;         if (fq == 0) part[(16 * mt + fr) * 8 + w] = s; }
; }
	v_mfma_f32_16x16x32_bf16 v[18:21], v[118:121], v[10:13], 0
	v_mfma_f32_16x16x32_bf16 v[10:13], v[94:97], v[10:13], 0
	s_waitcnt lgkmcnt(6)
	v_mfma_f32_16x16x32_bf16 v[18:21], v[114:117], v[14:17], v[18:21]
	v_mfma_f32_16x16x32_bf16 v[10:13], v[98:101], v[14:17], v[10:13]
	s_waitcnt lgkmcnt(5)
	v_mfma_f32_16x16x32_bf16 v[18:21], v[110:113], v[122:125], v[18:21]
	v_mfma_f32_16x16x32_bf16 v[10:13], v[82:85], v[122:125], v[10:13]
	s_waitcnt lgkmcnt(4)
	v_mfma_f32_16x16x32_bf16 v[18:21], v[106:109], v[126:129], v[18:21]
	v_mfma_f32_16x16x32_bf16 v[10:13], v[78:81], v[126:129], v[10:13]
	s_waitcnt lgkmcnt(3)
	v_mfma_f32_16x16x32_bf16 v[18:21], v[102:105], v[130:133], v[18:21]
	v_mfma_f32_16x16x32_bf16 v[10:13], v[74:77], v[130:133], v[10:13]
	s_waitcnt lgkmcnt(2)
	v_mfma_f32_16x16x32_bf16 v[18:21], v[90:93], v[134:137], v[18:21]
	v_mfma_f32_16x16x32_bf16 v[10:13], v[70:73], v[134:137], v[10:13]
	s_waitcnt lgkmcnt(1)
	v_mfma_f32_16x16x32_bf16 v[18:21], v[86:89], v[138:141], v[18:21]
	v_mfma_f32_16x16x32_bf16 v[10:13], v[66:69], v[138:141], v[10:13]
	s_waitcnt lgkmcnt(0)
	v_mfma_f32_16x16x32_bf16 v[22:25], v[2:5], v[142:145], v[18:21]
	v_mfma_f32_16x16x32_bf16 v[18:21], v[6:9], v[142:145], v[10:13]
	s_nop 4
	ds_read_b128 v[10:13], v0 offset:50688
	ds_read_b128 v[122:125], v0 offset:50752
	ds_read_b128 v[126:129], v0 offset:50816
	ds_read_b128 v[130:133], v0 offset:50880
	ds_read_b128 v[134:137], v0 offset:50944
	ds_read_b128 v[138:141], v0 offset:51008
	s_waitcnt lgkmcnt(5)
	v_mfma_f32_16x16x32_bf16 v[14:17], v[118:121], v[10:13], 0
	ds_read_b128 v[142:145], v0 offset:51072
	ds_read_b128 v[146:149], v0 offset:51136
	v_mfma_f32_16x16x32_bf16 v[10:13], v[94:97], v[10:13], 0
	s_waitcnt lgkmcnt(6)
	v_mfma_f32_16x16x32_bf16 v[14:17], v[114:117], v[122:125], v[14:17]
	v_mfma_f32_16x16x32_bf16 v[10:13], v[98:101], v[122:125], v[10:13]
	s_waitcnt lgkmcnt(5)
	v_mfma_f32_16x16x32_bf16 v[14:17], v[110:113], v[126:129], v[14:17]
	v_mfma_f32_16x16x32_bf16 v[10:13], v[82:85], v[126:129], v[10:13]
	ds_read_b128 v[122:125], v0 offset:59136
	ds_read_b128 v[126:129], v0 offset:59200
	s_waitcnt lgkmcnt(1)
	v_mfma_f32_16x16x32_bf16 v[118:121], v[118:121], v[122:125], 0
	v_mfma_f32_16x16x32_bf16 v[14:17], v[106:109], v[130:133], v[14:17]
	v_mfma_f32_16x16x32_bf16 v[10:13], v[78:81], v[130:133], v[10:13]
	s_waitcnt lgkmcnt(0)
	v_mfma_f32_16x16x32_bf16 v[114:117], v[114:117], v[126:129], v[118:121]
	s_nop 3
	ds_read_b128 v[118:121], v0 offset:59264
	ds_read_b128 v[130:133], v0 offset:59328
	s_waitcnt lgkmcnt(1)
	v_mfma_f32_16x16x32_bf16 v[110:113], v[110:113], v[118:121], v[114:117]
	s_waitcnt lgkmcnt(0)
	v_mfma_f32_16x16x32_bf16 v[106:109], v[106:109], v[130:133], v[110:113]
	s_nop 5
	ds_read_b128 v[110:113], v0 offset:59392
	ds_read_b128 v[114:117], v0 offset:59456
	v_mfma_f32_16x16x32_bf16 v[14:17], v[102:105], v[134:137], v[14:17]
	s_waitcnt lgkmcnt(1)
	v_mfma_f32_16x16x32_bf16 v[102:105], v[102:105], v[110:113], v[106:109]
	v_mfma_f32_16x16x32_bf16 v[14:17], v[90:93], v[138:141], v[14:17]
	s_waitcnt lgkmcnt(0)
	v_mfma_f32_16x16x32_bf16 v[90:93], v[90:93], v[114:117], v[102:105]
	s_nop 4
	ds_read_b128 v[102:105], v0 offset:59520
	ds_read_b128 v[106:109], v0 offset:59584
	v_mul_f32_e32 v0, v63, v63
	v_fmac_f32_e32 v0, v62, v62
	v_mfma_f32_16x16x32_bf16 v[14:17], v[86:89], v[142:145], v[14:17]
	s_waitcnt lgkmcnt(1)
	v_mfma_f32_16x16x32_bf16 v[86:89], v[86:89], v[102:105], v[90:93]
	v_mfma_f32_16x16x32_bf16 v[14:17], v[2:5], v[146:149], v[14:17]
	s_waitcnt lgkmcnt(0)
	v_mfma_f32_16x16x32_bf16 v[2:5], v[2:5], v[106:109], v[86:89]
	v_mfma_f32_16x16x32_bf16 v[86:89], v[94:97], v[122:125], 0
	v_mfma_f32_16x16x32_bf16 v[86:89], v[98:101], v[126:129], v[86:89]
	v_mfma_f32_16x16x32_bf16 v[82:85], v[82:85], v[118:121], v[86:89]
	v_mfma_f32_16x16x32_bf16 v[78:81], v[78:81], v[130:133], v[82:85]
	s_nop 5
	v_mul_f32_e32 v86, v65, v65
	v_fmac_f32_e32 v86, v64, v64
	v_add_f32_e32 v0, v0, v86
	v_mfma_f32_16x16x32_bf16 v[10:13], v[74:77], v[134:137], v[10:13]
	v_mul_f32_e32 v82, v59, v59
	v_fmac_f32_e32 v82, v58, v58
	v_mfma_f32_16x16x32_bf16 v[74:77], v[74:77], v[110:113], v[78:81]
	s_nop 2
	v_mul_f32_e32 v78, v61, v61
	v_fmac_f32_e32 v78, v60, v60
	v_add_f32_e32 v78, v82, v78
	v_mfma_f32_16x16x32_bf16 v[10:13], v[70:73], v[138:141], v[10:13]
	v_add_f32_e32 v0, v0, v78
	v_mfma_f32_16x16x32_bf16 v[70:73], v[70:73], v[114:117], v[74:77]
	s_nop 2
	ds_bpermute_b32 v74, v207, v0
	v_mfma_f32_16x16x32_bf16 v[10:13], v[66:69], v[142:145], v[10:13]
	s_waitcnt lgkmcnt(0)
	v_add_f32_e32 v0, v0, v74
	v_mfma_f32_16x16x32_bf16 v[68:71], v[66:69], v[102:105], v[70:73]
	ds_bpermute_b32 v66, v208, v0
	v_mfma_f32_16x16x32_bf16 v[10:13], v[6:9], v[146:149], v[10:13]
	v_mfma_f32_16x16x32_bf16 v[6:9], v[6:9], v[106:109], v[68:71]
	s_and_saveexec_b64 s[6:7], s[40:41]
	s_cbranch_execz .LBB0_300
	s_waitcnt lgkmcnt(0)
	v_add_f32_e32 v0, v0, v66
	ds_write_b32 v216, v0
